# 8-phase GEMM loops: s_setprio 1 moved in front of the phase barrier so that each compute segment opens directly with its first MFMA
# speedup vs baseline: 1.0027x; 1.0027x over previous
.LBB0_235:
	ds_read_b128 v[128:131], v173
	ds_read_b128 v[132:135], v173 offset:1024
	ds_read_b128 v[152:155], v173 offset:2048
	ds_read_b128 v[178:181], v173 offset:3072
	ds_read_b128 v[184:187], v174
	ds_read_b128 v[188:191], v174 offset:1024
	ds_read_b128 v[192:195], v174 offset:2048
	ds_read_b128 v[196:199], v174 offset:3072
	s_add_u32 s24, s38, 0xfff80080
	s_addc_u32 s25, s39, -1
	s_cmp_eq_u32 s63, 28
	s_cselect_b32 s47, s5, s25
	s_cselect_b32 s46, s6, s24
	s_cselect_b32 s41, s15, s62
	s_cselect_b32 s40, s17, s43
	v_lshl_add_u64 v[232:233], s[38:39], 0, v[144:145]
	s_add_i32 m0, s77, 0xc000
	ds_read_b128 v[200:203], v175
	ds_read_b128 v[204:207], v175 offset:1024
	ds_read_b128 v[208:211], v175 offset:2048
	ds_read_b128 v[212:215], v175 offset:3072
	ds_read_b128 v[216:219], v175 offset:4096
	ds_read_b128 v[220:223], v175 offset:5120
	ds_read_b128 v[224:227], v175 offset:6144
	ds_read_b128 v[228:231], v175 offset:7168
	global_load_lds_dwordx4 v[232:233], off
	v_lshl_add_u64 v[232:233], s[38:39], 0, v[146:147]
	s_add_i32 m0, s77, 0xe000
	s_nop 0
	global_load_lds_dwordx4 v[232:233], off
	s_waitcnt vmcnt(8)
	s_waitcnt lgkmcnt(0)
	s_setprio 1
	s_barrier
	v_mfma_f32_16x16x32_bf16 v[124:127], v[128:131], v[200:203], v[124:127]
	v_mfma_f32_16x16x32_bf16 v[120:123], v[152:155], v[200:203], v[120:123]
	v_mfma_f32_16x16x32_bf16 v[116:119], v[128:131], v[208:211], v[116:119]
	v_mfma_f32_16x16x32_bf16 v[112:115], v[152:155], v[208:211], v[112:115]
	v_mfma_f32_16x16x32_bf16 v[108:111], v[128:131], v[216:219], v[108:111]
	v_mfma_f32_16x16x32_bf16 v[104:107], v[152:155], v[216:219], v[104:107]
	v_mfma_f32_16x16x32_bf16 v[100:103], v[128:131], v[224:227], v[100:103]
	v_mfma_f32_16x16x32_bf16 v[96:99], v[152:155], v[224:227], v[96:99]
	v_mfma_f32_16x16x32_bf16 v[124:127], v[132:135], v[204:207], v[124:127]
	v_mfma_f32_16x16x32_bf16 v[120:123], v[178:181], v[204:207], v[120:123]
	v_mfma_f32_16x16x32_bf16 v[116:119], v[132:135], v[212:215], v[116:119]
	v_mfma_f32_16x16x32_bf16 v[112:115], v[178:181], v[212:215], v[112:115]
	v_mfma_f32_16x16x32_bf16 v[108:111], v[132:135], v[220:223], v[108:111]
	v_mfma_f32_16x16x32_bf16 v[104:107], v[178:181], v[220:223], v[104:107]
	v_mfma_f32_16x16x32_bf16 v[100:103], v[132:135], v[228:231], v[100:103]
	v_mfma_f32_16x16x32_bf16 v[96:99], v[178:181], v[228:231], v[96:99]
	s_setprio 0
	s_setprio 1
	v_mfma_f32_16x16x32_bf16 v[60:63], v[184:187], v[200:203], v[60:63]
	v_mfma_f32_16x16x32_bf16 v[56:59], v[192:195], v[200:203], v[56:59]
	v_mfma_f32_16x16x32_bf16 v[52:55], v[184:187], v[208:211], v[52:55]
	v_mfma_f32_16x16x32_bf16 v[48:51], v[192:195], v[208:211], v[48:51]
	v_mfma_f32_16x16x32_bf16 v[44:47], v[184:187], v[216:219], v[44:47]
	v_mfma_f32_16x16x32_bf16 v[40:43], v[192:195], v[216:219], v[40:43]
	v_mfma_f32_16x16x32_bf16 v[36:39], v[184:187], v[224:227], v[36:39]
	v_mfma_f32_16x16x32_bf16 v[32:35], v[192:195], v[224:227], v[32:35]
	v_mfma_f32_16x16x32_bf16 v[60:63], v[188:191], v[204:207], v[60:63]
	v_mfma_f32_16x16x32_bf16 v[56:59], v[196:199], v[204:207], v[56:59]
	v_mfma_f32_16x16x32_bf16 v[52:55], v[188:191], v[212:215], v[52:55]
	v_mfma_f32_16x16x32_bf16 v[48:51], v[196:199], v[212:215], v[48:51]
	v_mfma_f32_16x16x32_bf16 v[44:47], v[188:191], v[220:223], v[44:47]
	v_mfma_f32_16x16x32_bf16 v[40:43], v[196:199], v[220:223], v[40:43]
	v_mfma_f32_16x16x32_bf16 v[36:39], v[188:191], v[228:231], v[36:39]
	v_mfma_f32_16x16x32_bf16 v[32:35], v[196:199], v[228:231], v[32:35]
	s_setprio 0
	s_barrier
	s_add_i32 s24, s87, s76
	v_lshl_add_u64 v[232:233], s[40:41], 0, v[138:139]
	s_mov_b32 m0, s24
	ds_read_b128 v[200:203], v175 offset:16384
	ds_read_b128 v[204:207], v175 offset:17408
	ds_read_b128 v[208:211], v175 offset:18432
	ds_read_b128 v[212:215], v175 offset:19456
	ds_read_b128 v[216:219], v175 offset:20480
	ds_read_b128 v[220:223], v175 offset:21504
	ds_read_b128 v[224:227], v175 offset:22528
	ds_read_b128 v[228:231], v175 offset:23552
	global_load_lds_dwordx4 v[232:233], off
	s_add_i32 m0, s24, 0x2000
	s_add_u32 s24, s40, 0x80000
	v_lshl_add_u64 v[234:235], s[40:41], 0, v[142:143]
	s_addc_u32 s25, s41, 0
	s_add_i32 s26, s88, s76
	global_load_lds_dwordx4 v[234:235], off
	v_lshl_add_u64 v[236:237], s[24:25], 0, v[138:139]
	s_mov_b32 m0, s26
	v_lshl_add_u64 v[238:239], s[46:47], 0, v[140:141]
	global_load_lds_dwordx4 v[236:237], off
	v_lshl_add_u64 v[236:237], s[24:25], 0, v[142:143]
	s_add_i32 m0, s26, 0x2000
	s_nop 0
	global_load_lds_dwordx4 v[236:237], off
	v_lshl_add_u64 v[236:237], s[46:47], 0, v[136:137]
	s_mov_b32 m0, s77
	s_nop 0
	global_load_lds_dwordx4 v[236:237], off
	s_mov_b32 m0, s78
	s_nop 0
	global_load_lds_dwordx4 v[238:239], off
	s_waitcnt vmcnt(8)
	s_waitcnt lgkmcnt(0)
	s_setprio 1
	s_barrier
	v_mfma_f32_16x16x32_bf16 v[92:95], v[128:131], v[200:203], v[92:95]
	v_mfma_f32_16x16x32_bf16 v[88:91], v[152:155], v[200:203], v[88:91]
	v_mfma_f32_16x16x32_bf16 v[84:87], v[128:131], v[208:211], v[84:87]
	v_mfma_f32_16x16x32_bf16 v[80:83], v[152:155], v[208:211], v[80:83]
	v_mfma_f32_16x16x32_bf16 v[76:79], v[128:131], v[216:219], v[76:79]
	v_mfma_f32_16x16x32_bf16 v[72:75], v[152:155], v[216:219], v[72:75]
	v_mfma_f32_16x16x32_bf16 v[68:71], v[128:131], v[224:227], v[68:71]
	v_mfma_f32_16x16x32_bf16 v[64:67], v[152:155], v[224:227], v[64:67]
	v_mfma_f32_16x16x32_bf16 v[92:95], v[132:135], v[204:207], v[92:95]
	v_mfma_f32_16x16x32_bf16 v[88:91], v[178:181], v[204:207], v[88:91]
	v_mfma_f32_16x16x32_bf16 v[84:87], v[132:135], v[212:215], v[84:87]
	v_mfma_f32_16x16x32_bf16 v[80:83], v[178:181], v[212:215], v[80:83]
	v_mfma_f32_16x16x32_bf16 v[76:79], v[132:135], v[220:223], v[76:79]
	v_mfma_f32_16x16x32_bf16 v[72:75], v[178:181], v[220:223], v[72:75]
	v_mfma_f32_16x16x32_bf16 v[68:71], v[132:135], v[228:231], v[68:71]
	v_mfma_f32_16x16x32_bf16 v[64:67], v[178:181], v[228:231], v[64:67]
	s_setprio 0
	s_setprio 1
	v_mfma_f32_16x16x32_bf16 v[28:31], v[184:187], v[200:203], v[28:31]
	v_mfma_f32_16x16x32_bf16 v[24:27], v[192:195], v[200:203], v[24:27]
	v_mfma_f32_16x16x32_bf16 v[20:23], v[184:187], v[208:211], v[20:23]
	v_mfma_f32_16x16x32_bf16 v[16:19], v[192:195], v[208:211], v[16:19]
	v_mfma_f32_16x16x32_bf16 v[12:15], v[184:187], v[216:219], v[12:15]
	v_mfma_f32_16x16x32_bf16 v[8:11], v[192:195], v[216:219], v[8:11]
	v_mfma_f32_16x16x32_bf16 v[4:7], v[184:187], v[224:227], v[4:7]
	v_mfma_f32_16x16x32_bf16 v[0:3], v[192:195], v[224:227], v[0:3]
	v_mfma_f32_16x16x32_bf16 v[28:31], v[188:191], v[204:207], v[28:31]
	v_mfma_f32_16x16x32_bf16 v[24:27], v[196:199], v[204:207], v[24:27]
	v_mfma_f32_16x16x32_bf16 v[20:23], v[188:191], v[212:215], v[20:23]
	v_mfma_f32_16x16x32_bf16 v[16:19], v[196:199], v[212:215], v[16:19]
	v_mfma_f32_16x16x32_bf16 v[12:15], v[188:191], v[220:223], v[12:15]
	v_mfma_f32_16x16x32_bf16 v[8:11], v[196:199], v[220:223], v[8:11]
	v_mfma_f32_16x16x32_bf16 v[4:7], v[188:191], v[228:231], v[4:7]
	v_mfma_f32_16x16x32_bf16 v[0:3], v[196:199], v[228:231], v[0:3]
	s_setprio 0
	s_barrier
	s_add_i32 s26, 0, 0x18000
	v_add_u32_e32 v177, s26, v166
	s_add_i32 s27, 0, 0x1c000
	ds_read_b128 v[128:131], v177
	ds_read_b128 v[132:135], v177 offset:1024
	ds_read_b128 v[152:155], v177 offset:2048
	ds_read_b128 v[178:181], v177 offset:3072
	v_add_u32_e32 v177, s27, v166
	ds_read_b128 v[184:187], v177
	ds_read_b128 v[188:191], v177 offset:1024
	ds_read_b128 v[192:195], v177 offset:2048
	ds_read_b128 v[196:199], v177 offset:3072
	s_add_u32 s24, s46, 0x80000
	s_addc_u32 s25, s47, 0
	s_mov_b32 m0, s79
	v_lshl_add_u64 v[240:241], s[24:25], 0, v[136:137]
	ds_read_b128 v[200:203], v175 offset:32768
	ds_read_b128 v[204:207], v175 offset:33792
	ds_read_b128 v[208:211], v175 offset:34816
	ds_read_b128 v[212:215], v175 offset:35840
	ds_read_b128 v[216:219], v175 offset:36864
	ds_read_b128 v[220:223], v175 offset:37888
	ds_read_b128 v[224:227], v175 offset:38912
	ds_read_b128 v[228:231], v175 offset:39936
	global_load_lds_dwordx4 v[240:241], off
	v_lshl_add_u64 v[240:241], s[24:25], 0, v[140:141]
	s_mov_b32 m0, s80
	s_nop 0
	global_load_lds_dwordx4 v[240:241], off
	s_waitcnt vmcnt(8)
	s_waitcnt lgkmcnt(0)
	s_setprio 1
	s_barrier
	v_mfma_f32_16x16x32_bf16 v[124:127], v[128:131], v[200:203], v[124:127]
	v_mfma_f32_16x16x32_bf16 v[120:123], v[152:155], v[200:203], v[120:123]
	v_mfma_f32_16x16x32_bf16 v[116:119], v[128:131], v[208:211], v[116:119]
	v_mfma_f32_16x16x32_bf16 v[112:115], v[152:155], v[208:211], v[112:115]
	v_mfma_f32_16x16x32_bf16 v[108:111], v[128:131], v[216:219], v[108:111]
	v_mfma_f32_16x16x32_bf16 v[104:107], v[152:155], v[216:219], v[104:107]
	v_mfma_f32_16x16x32_bf16 v[100:103], v[128:131], v[224:227], v[100:103]
	v_mfma_f32_16x16x32_bf16 v[96:99], v[152:155], v[224:227], v[96:99]
	v_mfma_f32_16x16x32_bf16 v[124:127], v[132:135], v[204:207], v[124:127]
	v_mfma_f32_16x16x32_bf16 v[120:123], v[178:181], v[204:207], v[120:123]
	v_mfma_f32_16x16x32_bf16 v[116:119], v[132:135], v[212:215], v[116:119]
	v_mfma_f32_16x16x32_bf16 v[112:115], v[178:181], v[212:215], v[112:115]
	v_mfma_f32_16x16x32_bf16 v[108:111], v[132:135], v[220:223], v[108:111]
	v_mfma_f32_16x16x32_bf16 v[104:107], v[178:181], v[220:223], v[104:107]
	v_mfma_f32_16x16x32_bf16 v[100:103], v[132:135], v[228:231], v[100:103]
	v_mfma_f32_16x16x32_bf16 v[96:99], v[178:181], v[228:231], v[96:99]
	s_setprio 0
	s_setprio 1
	v_mfma_f32_16x16x32_bf16 v[60:63], v[184:187], v[200:203], v[60:63]
	v_mfma_f32_16x16x32_bf16 v[56:59], v[192:195], v[200:203], v[56:59]
	v_mfma_f32_16x16x32_bf16 v[52:55], v[184:187], v[208:211], v[52:55]
	v_mfma_f32_16x16x32_bf16 v[48:51], v[192:195], v[208:211], v[48:51]
	v_mfma_f32_16x16x32_bf16 v[44:47], v[184:187], v[216:219], v[44:47]
	v_mfma_f32_16x16x32_bf16 v[40:43], v[192:195], v[216:219], v[40:43]
	v_mfma_f32_16x16x32_bf16 v[36:39], v[184:187], v[224:227], v[36:39]
	v_mfma_f32_16x16x32_bf16 v[32:35], v[192:195], v[224:227], v[32:35]
	v_mfma_f32_16x16x32_bf16 v[60:63], v[188:191], v[204:207], v[60:63]
	v_mfma_f32_16x16x32_bf16 v[56:59], v[196:199], v[204:207], v[56:59]
	v_mfma_f32_16x16x32_bf16 v[52:55], v[188:191], v[212:215], v[52:55]
	v_mfma_f32_16x16x32_bf16 v[48:51], v[196:199], v[212:215], v[48:51]
	v_mfma_f32_16x16x32_bf16 v[44:47], v[188:191], v[220:223], v[44:47]
	v_mfma_f32_16x16x32_bf16 v[40:43], v[196:199], v[220:223], v[40:43]
	v_mfma_f32_16x16x32_bf16 v[36:39], v[188:191], v[228:231], v[36:39]
	v_mfma_f32_16x16x32_bf16 v[32:35], v[196:199], v[228:231], v[32:35]
	s_setprio 0
	s_barrier
	s_add_i32 s24, s26, s76
	v_lshl_add_u64 v[232:233], v[232:233], 0, s[10:11]
	s_mov_b32 m0, s24
	ds_read_b128 v[200:203], v175 offset:49152
	ds_read_b128 v[204:207], v175 offset:50176
	ds_read_b128 v[208:211], v175 offset:51200
	ds_read_b128 v[212:215], v175 offset:52224
	ds_read_b128 v[216:219], v175 offset:53248
	ds_read_b128 v[220:223], v175 offset:54272
	ds_read_b128 v[224:227], v175 offset:55296
	ds_read_b128 v[228:231], v175 offset:56320
	global_load_lds_dwordx4 v[232:233], off
	s_add_i32 m0, s24, 0x2000
	s_add_u32 s24, s40, 0x80080
	v_lshl_add_u64 v[232:233], v[234:235], 0, s[10:11]
	s_addc_u32 s25, s41, 0
	s_add_i32 s26, s27, s76
	global_load_lds_dwordx4 v[232:233], off
	v_lshl_add_u64 v[232:233], s[24:25], 0, v[138:139]
	s_mov_b32 m0, s26
	s_nop 0
	global_load_lds_dwordx4 v[232:233], off
	v_lshl_add_u64 v[232:233], s[24:25], 0, v[142:143]
	s_add_i32 m0, s26, 0x2000
	s_nop 0
	global_load_lds_dwordx4 v[232:233], off
	v_lshl_add_u64 v[232:233], v[236:237], 0, s[10:11]
	s_mov_b32 m0, s81
	s_nop 0
	global_load_lds_dwordx4 v[232:233], off
	v_lshl_add_u64 v[232:233], v[238:239], 0, s[10:11]
	s_mov_b32 m0, s82
	s_nop 0
	global_load_lds_dwordx4 v[232:233], off
	s_waitcnt vmcnt(8)
	s_waitcnt lgkmcnt(0)
	s_setprio 1
	s_barrier
	v_mfma_f32_16x16x32_bf16 v[92:95], v[128:131], v[200:203], v[92:95]
	v_mfma_f32_16x16x32_bf16 v[88:91], v[152:155], v[200:203], v[88:91]
	v_mfma_f32_16x16x32_bf16 v[84:87], v[128:131], v[208:211], v[84:87]
	v_mfma_f32_16x16x32_bf16 v[80:83], v[152:155], v[208:211], v[80:83]
	v_mfma_f32_16x16x32_bf16 v[76:79], v[128:131], v[216:219], v[76:79]
	v_mfma_f32_16x16x32_bf16 v[72:75], v[152:155], v[216:219], v[72:75]
	v_mfma_f32_16x16x32_bf16 v[68:71], v[128:131], v[224:227], v[68:71]
	v_mfma_f32_16x16x32_bf16 v[64:67], v[152:155], v[224:227], v[64:67]
	v_mfma_f32_16x16x32_bf16 v[92:95], v[132:135], v[204:207], v[92:95]
	v_mfma_f32_16x16x32_bf16 v[88:91], v[178:181], v[204:207], v[88:91]
	v_mfma_f32_16x16x32_bf16 v[84:87], v[132:135], v[212:215], v[84:87]
	v_mfma_f32_16x16x32_bf16 v[80:83], v[178:181], v[212:215], v[80:83]
	v_mfma_f32_16x16x32_bf16 v[76:79], v[132:135], v[220:223], v[76:79]
	v_mfma_f32_16x16x32_bf16 v[72:75], v[178:181], v[220:223], v[72:75]
	v_mfma_f32_16x16x32_bf16 v[68:71], v[132:135], v[228:231], v[68:71]
	v_mfma_f32_16x16x32_bf16 v[64:67], v[178:181], v[228:231], v[64:67]
	s_setprio 0
	s_setprio 1
	v_mfma_f32_16x16x32_bf16 v[28:31], v[184:187], v[200:203], v[28:31]
	v_mfma_f32_16x16x32_bf16 v[24:27], v[192:195], v[200:203], v[24:27]
	v_mfma_f32_16x16x32_bf16 v[20:23], v[184:187], v[208:211], v[20:23]
	v_mfma_f32_16x16x32_bf16 v[16:19], v[192:195], v[208:211], v[16:19]
	v_mfma_f32_16x16x32_bf16 v[12:15], v[184:187], v[216:219], v[12:15]
	v_mfma_f32_16x16x32_bf16 v[8:11], v[192:195], v[216:219], v[8:11]
	v_mfma_f32_16x16x32_bf16 v[4:7], v[184:187], v[224:227], v[4:7]
	v_mfma_f32_16x16x32_bf16 v[0:3], v[192:195], v[224:227], v[0:3]
	v_mfma_f32_16x16x32_bf16 v[28:31], v[188:191], v[204:207], v[28:31]
	v_mfma_f32_16x16x32_bf16 v[24:27], v[196:199], v[204:207], v[24:27]
	v_mfma_f32_16x16x32_bf16 v[20:23], v[188:191], v[212:215], v[20:23]
	v_mfma_f32_16x16x32_bf16 v[16:19], v[196:199], v[212:215], v[16:19]
	v_mfma_f32_16x16x32_bf16 v[12:15], v[188:191], v[220:223], v[12:15]
	v_mfma_f32_16x16x32_bf16 v[8:11], v[196:199], v[220:223], v[8:11]
	v_mfma_f32_16x16x32_bf16 v[4:7], v[188:191], v[228:231], v[4:7]
	v_mfma_f32_16x16x32_bf16 v[0:3], v[196:199], v[228:231], v[0:3]
	s_setprio 0
	s_barrier
	s_add_i32 s63, s63, 2
	s_add_u32 s38, s38, 0x100
	s_addc_u32 s39, s39, 0
	s_add_u32 s43, s43, 0x100
	s_addc_u32 s62, s62, 0
	s_cmp_gt_u32 s63, 29
	s_cbranch_scc0 .LBB0_235
	s_and_b64 vcc, exec, s[12:13]
	s_cbranch_vccz .LBB0_238
	s_barrier

.LBB0_349:
	ds_read_b128 v[16:19], v186
	ds_read_b128 v[20:23], v186 offset:1024
	ds_read_b128 v[24:27], v186 offset:2048
	ds_read_b128 v[28:31], v186 offset:3072
	ds_read_b128 v[0:3], v187
	ds_read_b128 v[4:7], v187 offset:1024
	ds_read_b128 v[8:11], v187 offset:2048
	ds_read_b128 v[12:15], v187 offset:3072
	s_add_u32 s24, s62, 0xfffc0080
	s_addc_u32 s25, s63, -1
	s_cmp_eq_u32 s71, 12
	s_cselect_b32 s69, s1, s25
	s_cselect_b32 s68, s8, s24
	s_cselect_b32 s67, s23, s70
	s_cselect_b32 s66, s39, s65
	v_lshl_add_u64 v[214:215], s[62:63], 0, v[170:171]
	s_add_i32 m0, s81, 0xc000
	ds_read_b128 v[174:177], v188
	ds_read_b128 v[178:181], v188 offset:1024
	ds_read_b128 v[190:193], v188 offset:2048
	ds_read_b128 v[194:197], v188 offset:3072
	ds_read_b128 v[198:201], v188 offset:4096
	ds_read_b128 v[202:205], v188 offset:5120
	ds_read_b128 v[206:209], v188 offset:6144
	ds_read_b128 v[210:213], v188 offset:7168
	global_load_lds_dwordx4 v[214:215], off
	v_lshl_add_u64 v[214:215], s[62:63], 0, v[172:173]
	s_add_i32 m0, s81, 0xe000
	s_nop 0
	global_load_lds_dwordx4 v[214:215], off
	s_waitcnt vmcnt(8)
	s_waitcnt lgkmcnt(0)
	s_setprio 1
	s_barrier
	v_mfma_scale_f32_16x16x128_f8f6f4 v[156:159], v[16:23], v[174:181], v[156:159], v189, v189 op_sel_hi:[0,0,0]
	v_mfma_scale_f32_16x16x128_f8f6f4 v[152:155], v[24:31], v[174:181], v[152:155], v189, v189 op_sel_hi:[0,0,0]
	v_mfma_scale_f32_16x16x128_f8f6f4 v[148:151], v[16:23], v[190:197], v[148:151], v189, v189 op_sel_hi:[0,0,0]
	v_mfma_scale_f32_16x16x128_f8f6f4 v[144:147], v[24:31], v[190:197], v[144:147], v189, v189 op_sel_hi:[0,0,0]
	v_mfma_scale_f32_16x16x128_f8f6f4 v[140:143], v[16:23], v[198:205], v[140:143], v189, v189 op_sel_hi:[0,0,0]
	v_mfma_scale_f32_16x16x128_f8f6f4 v[136:139], v[24:31], v[198:205], v[136:139], v189, v189 op_sel_hi:[0,0,0]
	v_mfma_scale_f32_16x16x128_f8f6f4 v[132:135], v[16:23], v[206:213], v[132:135], v189, v189 op_sel_hi:[0,0,0]
	v_mfma_scale_f32_16x16x128_f8f6f4 v[128:131], v[24:31], v[206:213], v[128:131], v189, v189 op_sel_hi:[0,0,0]
	s_setprio 0
	s_setprio 1
	v_mfma_scale_f32_16x16x128_f8f6f4 v[92:95], v[0:7], v[174:181], v[92:95], v189, v189 op_sel_hi:[0,0,0]
	v_mfma_scale_f32_16x16x128_f8f6f4 v[88:91], v[8:15], v[174:181], v[88:91], v189, v189 op_sel_hi:[0,0,0]
	v_mfma_scale_f32_16x16x128_f8f6f4 v[84:87], v[0:7], v[190:197], v[84:87], v189, v189 op_sel_hi:[0,0,0]
	v_mfma_scale_f32_16x16x128_f8f6f4 v[80:83], v[8:15], v[190:197], v[80:83], v189, v189 op_sel_hi:[0,0,0]
	v_mfma_scale_f32_16x16x128_f8f6f4 v[76:79], v[0:7], v[198:205], v[76:79], v189, v189 op_sel_hi:[0,0,0]
	v_mfma_scale_f32_16x16x128_f8f6f4 v[72:75], v[8:15], v[198:205], v[72:75], v189, v189 op_sel_hi:[0,0,0]
	v_mfma_scale_f32_16x16x128_f8f6f4 v[68:71], v[0:7], v[206:213], v[68:71], v189, v189 op_sel_hi:[0,0,0]
	v_mfma_scale_f32_16x16x128_f8f6f4 v[64:67], v[8:15], v[206:213], v[64:67], v189, v189 op_sel_hi:[0,0,0]
	s_setprio 0
	s_barrier
	s_add_i32 s24, s90, s80
	v_lshl_add_u64 v[174:175], s[66:67], 0, v[162:163]
	s_mov_b32 m0, s24
	ds_read_b128 v[190:193], v188 offset:16384
	ds_read_b128 v[194:197], v188 offset:17408
	ds_read_b128 v[198:201], v188 offset:18432
	ds_read_b128 v[202:205], v188 offset:19456
	ds_read_b128 v[206:209], v188 offset:20480
	ds_read_b128 v[210:213], v188 offset:21504
	ds_read_b128 v[214:217], v188 offset:22528
	ds_read_b128 v[218:221], v188 offset:23552
	global_load_lds_dwordx4 v[174:175], off
	s_add_i32 m0, s24, 0x2000
	s_add_u32 s24, s66, 0x40000
	v_lshl_add_u64 v[176:177], s[66:67], 0, v[166:167]
	s_addc_u32 s25, s67, 0
	s_add_i32 s26, s91, s80
	global_load_lds_dwordx4 v[176:177], off
	v_lshl_add_u64 v[178:179], s[24:25], 0, v[162:163]
	s_mov_b32 m0, s26
	v_lshl_add_u64 v[180:181], s[68:69], 0, v[164:165]
	global_load_lds_dwordx4 v[178:179], off
	v_lshl_add_u64 v[178:179], s[24:25], 0, v[166:167]
	s_add_i32 m0, s26, 0x2000
	s_nop 0
	global_load_lds_dwordx4 v[178:179], off
	v_lshl_add_u64 v[178:179], s[68:69], 0, v[160:161]
	s_mov_b32 m0, s81
	s_nop 0
	global_load_lds_dwordx4 v[178:179], off
	s_mov_b32 m0, s82
	s_nop 0
	global_load_lds_dwordx4 v[180:181], off
	s_waitcnt vmcnt(8)
	s_waitcnt lgkmcnt(0)
	s_setprio 1
	s_barrier
	v_mfma_scale_f32_16x16x128_f8f6f4 v[124:127], v[16:23], v[190:197], v[124:127], v189, v189 op_sel_hi:[0,0,0]
	v_mfma_scale_f32_16x16x128_f8f6f4 v[120:123], v[24:31], v[190:197], v[120:123], v189, v189 op_sel_hi:[0,0,0]
	v_mfma_scale_f32_16x16x128_f8f6f4 v[116:119], v[16:23], v[198:205], v[116:119], v189, v189 op_sel_hi:[0,0,0]
	v_mfma_scale_f32_16x16x128_f8f6f4 v[112:115], v[24:31], v[198:205], v[112:115], v189, v189 op_sel_hi:[0,0,0]
	v_mfma_scale_f32_16x16x128_f8f6f4 v[108:111], v[16:23], v[206:213], v[108:111], v189, v189 op_sel_hi:[0,0,0]
	v_mfma_scale_f32_16x16x128_f8f6f4 v[104:107], v[24:31], v[206:213], v[104:107], v189, v189 op_sel_hi:[0,0,0]
	v_mfma_scale_f32_16x16x128_f8f6f4 v[100:103], v[16:23], v[214:221], v[100:103], v189, v189 op_sel_hi:[0,0,0]
	v_mfma_scale_f32_16x16x128_f8f6f4 v[96:99], v[24:31], v[214:221], v[96:99], v189, v189 op_sel_hi:[0,0,0]
	s_setprio 0
	s_setprio 1
	v_mfma_scale_f32_16x16x128_f8f6f4 v[60:63], v[0:7], v[190:197], v[60:63], v189, v189 op_sel_hi:[0,0,0]
	v_mfma_scale_f32_16x16x128_f8f6f4 v[56:59], v[8:15], v[190:197], v[56:59], v189, v189 op_sel_hi:[0,0,0]
	v_mfma_scale_f32_16x16x128_f8f6f4 v[52:55], v[0:7], v[198:205], v[52:55], v189, v189 op_sel_hi:[0,0,0]
	v_mfma_scale_f32_16x16x128_f8f6f4 v[48:51], v[8:15], v[198:205], v[48:51], v189, v189 op_sel_hi:[0,0,0]
	v_mfma_scale_f32_16x16x128_f8f6f4 v[44:47], v[0:7], v[206:213], v[44:47], v189, v189 op_sel_hi:[0,0,0]
	v_mfma_scale_f32_16x16x128_f8f6f4 v[40:43], v[8:15], v[206:213], v[40:43], v189, v189 op_sel_hi:[0,0,0]
	v_mfma_scale_f32_16x16x128_f8f6f4 v[36:39], v[0:7], v[214:221], v[36:39], v189, v189 op_sel_hi:[0,0,0]
	v_mfma_scale_f32_16x16x128_f8f6f4 v[32:35], v[8:15], v[214:221], v[32:35], v189, v189 op_sel_hi:[0,0,0]
	s_setprio 0
	s_barrier
	s_add_i32 s26, 0, 0x18000
	s_add_i32 s27, 0, 0x1c000
	v_add_u32_e32 v12, s26, v184
	v_add_u32_e32 v28, s27, v184
	ds_read_b128 v[0:3], v12
	ds_read_b128 v[4:7], v12 offset:1024
	ds_read_b128 v[8:11], v12 offset:2048
	ds_read_b128 v[12:15], v12 offset:3072
	ds_read_b128 v[16:19], v28
	ds_read_b128 v[20:23], v28 offset:1024
	ds_read_b128 v[24:27], v28 offset:2048
	ds_read_b128 v[28:31], v28 offset:3072
	s_add_u32 s24, s68, 0x40000
	s_addc_u32 s25, s69, 0
	s_mov_b32 m0, s83
	v_lshl_add_u64 v[222:223], s[24:25], 0, v[160:161]
	ds_read_b128 v[190:193], v188 offset:32768
	ds_read_b128 v[194:197], v188 offset:33792
	ds_read_b128 v[198:201], v188 offset:34816
	ds_read_b128 v[202:205], v188 offset:35840
	ds_read_b128 v[206:209], v188 offset:36864
	ds_read_b128 v[210:213], v188 offset:37888
	ds_read_b128 v[214:217], v188 offset:38912
	ds_read_b128 v[218:221], v188 offset:39936
	global_load_lds_dwordx4 v[222:223], off
	v_lshl_add_u64 v[222:223], s[24:25], 0, v[164:165]
	s_mov_b32 m0, s84
	s_nop 0
	global_load_lds_dwordx4 v[222:223], off
	s_waitcnt vmcnt(8)
	s_waitcnt lgkmcnt(0)
	s_setprio 1
	s_barrier
	v_mfma_scale_f32_16x16x128_f8f6f4 v[156:159], v[0:7], v[190:197], v[156:159], v189, v189 op_sel_hi:[0,0,0]
	v_mfma_scale_f32_16x16x128_f8f6f4 v[152:155], v[8:15], v[190:197], v[152:155], v189, v189 op_sel_hi:[0,0,0]
	v_mfma_scale_f32_16x16x128_f8f6f4 v[148:151], v[0:7], v[198:205], v[148:151], v189, v189 op_sel_hi:[0,0,0]
	v_mfma_scale_f32_16x16x128_f8f6f4 v[144:147], v[8:15], v[198:205], v[144:147], v189, v189 op_sel_hi:[0,0,0]
	v_mfma_scale_f32_16x16x128_f8f6f4 v[140:143], v[0:7], v[206:213], v[140:143], v189, v189 op_sel_hi:[0,0,0]
	v_mfma_scale_f32_16x16x128_f8f6f4 v[136:139], v[8:15], v[206:213], v[136:139], v189, v189 op_sel_hi:[0,0,0]
	v_mfma_scale_f32_16x16x128_f8f6f4 v[132:135], v[0:7], v[214:221], v[132:135], v189, v189 op_sel_hi:[0,0,0]
	v_mfma_scale_f32_16x16x128_f8f6f4 v[128:131], v[8:15], v[214:221], v[128:131], v189, v189 op_sel_hi:[0,0,0]
	s_setprio 0
	s_setprio 1
	v_mfma_scale_f32_16x16x128_f8f6f4 v[92:95], v[16:23], v[190:197], v[92:95], v189, v189 op_sel_hi:[0,0,0]
	v_mfma_scale_f32_16x16x128_f8f6f4 v[88:91], v[24:31], v[190:197], v[88:91], v189, v189 op_sel_hi:[0,0,0]
	v_mfma_scale_f32_16x16x128_f8f6f4 v[84:87], v[16:23], v[198:205], v[84:87], v189, v189 op_sel_hi:[0,0,0]
	v_mfma_scale_f32_16x16x128_f8f6f4 v[80:83], v[24:31], v[198:205], v[80:83], v189, v189 op_sel_hi:[0,0,0]
	v_mfma_scale_f32_16x16x128_f8f6f4 v[76:79], v[16:23], v[206:213], v[76:79], v189, v189 op_sel_hi:[0,0,0]
	v_mfma_scale_f32_16x16x128_f8f6f4 v[72:75], v[24:31], v[206:213], v[72:75], v189, v189 op_sel_hi:[0,0,0]
	v_mfma_scale_f32_16x16x128_f8f6f4 v[68:71], v[16:23], v[214:221], v[68:71], v189, v189 op_sel_hi:[0,0,0]
	v_mfma_scale_f32_16x16x128_f8f6f4 v[64:67], v[24:31], v[214:221], v[64:67], v189, v189 op_sel_hi:[0,0,0]
	s_setprio 0
	s_barrier
	s_add_i32 s24, s26, s80
	v_lshl_add_u64 v[174:175], v[174:175], 0, s[12:13]
	s_mov_b32 m0, s24
	ds_read_b128 v[190:193], v188 offset:49152
	ds_read_b128 v[194:197], v188 offset:50176
	ds_read_b128 v[198:201], v188 offset:51200
	ds_read_b128 v[202:205], v188 offset:52224
	ds_read_b128 v[206:209], v188 offset:53248
	ds_read_b128 v[210:213], v188 offset:54272
	ds_read_b128 v[214:217], v188 offset:55296
	ds_read_b128 v[218:221], v188 offset:56320
	global_load_lds_dwordx4 v[174:175], off
	s_add_i32 m0, s24, 0x2000
	s_add_u32 s24, s66, 0x40080
	v_lshl_add_u64 v[174:175], v[176:177], 0, s[12:13]
	s_addc_u32 s25, s67, 0
	s_add_i32 s26, s27, s80
	global_load_lds_dwordx4 v[174:175], off
	v_lshl_add_u64 v[174:175], s[24:25], 0, v[162:163]
	s_mov_b32 m0, s26
	s_nop 0
	global_load_lds_dwordx4 v[174:175], off
	v_lshl_add_u64 v[174:175], s[24:25], 0, v[166:167]
	s_add_i32 m0, s26, 0x2000
	s_nop 0
	global_load_lds_dwordx4 v[174:175], off
	v_lshl_add_u64 v[174:175], v[178:179], 0, s[12:13]
	s_mov_b32 m0, s86
	s_nop 0
	global_load_lds_dwordx4 v[174:175], off
	v_lshl_add_u64 v[174:175], v[180:181], 0, s[12:13]
	s_mov_b32 m0, s87
	s_nop 0
	global_load_lds_dwordx4 v[174:175], off
	s_waitcnt vmcnt(8)
	s_waitcnt lgkmcnt(0)
	s_setprio 1
	s_barrier
	v_mfma_scale_f32_16x16x128_f8f6f4 v[124:127], v[0:7], v[190:197], v[124:127], v189, v189 op_sel_hi:[0,0,0]
	v_mfma_scale_f32_16x16x128_f8f6f4 v[120:123], v[8:15], v[190:197], v[120:123], v189, v189 op_sel_hi:[0,0,0]
	v_mfma_scale_f32_16x16x128_f8f6f4 v[116:119], v[0:7], v[198:205], v[116:119], v189, v189 op_sel_hi:[0,0,0]
	v_mfma_scale_f32_16x16x128_f8f6f4 v[112:115], v[8:15], v[198:205], v[112:115], v189, v189 op_sel_hi:[0,0,0]
	v_mfma_scale_f32_16x16x128_f8f6f4 v[108:111], v[0:7], v[206:213], v[108:111], v189, v189 op_sel_hi:[0,0,0]
	v_mfma_scale_f32_16x16x128_f8f6f4 v[104:107], v[8:15], v[206:213], v[104:107], v189, v189 op_sel_hi:[0,0,0]
	v_mfma_scale_f32_16x16x128_f8f6f4 v[100:103], v[0:7], v[214:221], v[100:103], v189, v189 op_sel_hi:[0,0,0]
	v_mfma_scale_f32_16x16x128_f8f6f4 v[96:99], v[8:15], v[214:221], v[96:99], v189, v189 op_sel_hi:[0,0,0]
	s_setprio 0
	s_setprio 1
	v_mfma_scale_f32_16x16x128_f8f6f4 v[60:63], v[16:23], v[190:197], v[60:63], v189, v189 op_sel_hi:[0,0,0]
	v_mfma_scale_f32_16x16x128_f8f6f4 v[56:59], v[24:31], v[190:197], v[56:59], v189, v189 op_sel_hi:[0,0,0]
	v_mfma_scale_f32_16x16x128_f8f6f4 v[52:55], v[16:23], v[198:205], v[52:55], v189, v189 op_sel_hi:[0,0,0]
	v_mfma_scale_f32_16x16x128_f8f6f4 v[48:51], v[24:31], v[198:205], v[48:51], v189, v189 op_sel_hi:[0,0,0]
	v_mfma_scale_f32_16x16x128_f8f6f4 v[44:47], v[16:23], v[206:213], v[44:47], v189, v189 op_sel_hi:[0,0,0]
	v_mfma_scale_f32_16x16x128_f8f6f4 v[40:43], v[24:31], v[206:213], v[40:43], v189, v189 op_sel_hi:[0,0,0]
	v_mfma_scale_f32_16x16x128_f8f6f4 v[36:39], v[16:23], v[214:221], v[36:39], v189, v189 op_sel_hi:[0,0,0]
	v_mfma_scale_f32_16x16x128_f8f6f4 v[32:35], v[24:31], v[214:221], v[32:35], v189, v189 op_sel_hi:[0,0,0]
	s_setprio 0
	s_barrier
	s_add_i32 s71, s71, 2
	s_add_u32 s62, s62, 0x100
	s_addc_u32 s63, s63, 0
	s_add_u32 s65, s65, 0x100
	s_addc_u32 s70, s70, 0
	s_cmp_gt_u32 s71, 13
	s_cbranch_scc0 .LBB0_349
	s_and_b64 vcc, exec, s[18:19]
	s_cbranch_vccz .LBB0_352
	s_barrier

.LBB0_656:
	v_add_u32_e32 v1, s69, v177
	ds_read_b128 v[132:135], v1
	ds_read_b128 v[136:139], v1 offset:1024
	ds_read_b128 v[140:143], v1 offset:2048
	ds_read_b128 v[144:147], v1 offset:3072
	v_add_u32_e32 v1, s70, v177
	s_add_u32 s28, s26, s38
	ds_read_b128 v[180:183], v1
	ds_read_b128 v[184:187], v1 offset:1024
	ds_read_b128 v[188:191], v1 offset:2048
	ds_read_b128 v[192:195], v1 offset:3072
	s_addc_u32 s29, s27, s39
	s_add_u32 s28, s28, 0x100
	s_addc_u32 s29, s29, 0
	s_add_u32 s30, s73, s38
	s_addc_u32 s31, s74, s39
	s_cmpk_eq_i32 s38, 0xf00
	s_cselect_b32 s43, s19, s29
	s_cselect_b32 s42, s71, s28
	s_cselect_b32 s41, s17, s31
	s_cselect_b32 s40, s72, s30
	v_lshl_add_u64 v[2:3], v[170:171], 0, s[38:39]
	s_add_i32 m0, s50, 0xc000
	ds_read_b128 v[196:199], v179
	ds_read_b128 v[200:203], v179 offset:1024
	ds_read_b128 v[204:207], v179 offset:2048
	ds_read_b128 v[208:211], v179 offset:3072
	ds_read_b128 v[212:215], v179 offset:4096
	ds_read_b128 v[216:219], v179 offset:5120
	ds_read_b128 v[220:223], v179 offset:6144
	ds_read_b128 v[224:227], v179 offset:7168
	global_load_lds_dwordx4 v[2:3], off
	v_lshl_add_u64 v[2:3], v[172:173], 0, s[38:39]
	s_add_i32 m0, s50, 0xe000
	s_nop 0
	global_load_lds_dwordx4 v[2:3], off
	s_waitcnt vmcnt(8)
	s_waitcnt lgkmcnt(0)
	s_setprio 1
	s_barrier
	v_mfma_f32_16x16x32_bf16 v[128:131], v[132:135], v[196:199], v[128:131]
	v_mfma_f32_16x16x32_bf16 v[124:127], v[140:143], v[196:199], v[124:127]
	v_mfma_f32_16x16x32_bf16 v[112:115], v[132:135], v[204:207], v[112:115]
	v_mfma_f32_16x16x32_bf16 v[108:111], v[140:143], v[204:207], v[108:111]
	v_mfma_f32_16x16x32_bf16 v[96:99], v[132:135], v[212:215], v[96:99]
	v_mfma_f32_16x16x32_bf16 v[92:95], v[140:143], v[212:215], v[92:95]
	v_mfma_f32_16x16x32_bf16 v[80:83], v[132:135], v[220:223], v[80:83]
	v_mfma_f32_16x16x32_bf16 v[76:79], v[140:143], v[220:223], v[76:79]
	v_mfma_f32_16x16x32_bf16 v[128:131], v[136:139], v[200:203], v[128:131]
	v_mfma_f32_16x16x32_bf16 v[124:127], v[144:147], v[200:203], v[124:127]
	v_mfma_f32_16x16x32_bf16 v[112:115], v[136:139], v[208:211], v[112:115]
	v_mfma_f32_16x16x32_bf16 v[108:111], v[144:147], v[208:211], v[108:111]
	v_mfma_f32_16x16x32_bf16 v[96:99], v[136:139], v[216:219], v[96:99]
	v_mfma_f32_16x16x32_bf16 v[92:95], v[144:147], v[216:219], v[92:95]
	v_mfma_f32_16x16x32_bf16 v[80:83], v[136:139], v[224:227], v[80:83]
	v_mfma_f32_16x16x32_bf16 v[76:79], v[144:147], v[224:227], v[76:79]
	s_setprio 0
	s_setprio 1
	v_mfma_f32_16x16x32_bf16 v[120:123], v[180:183], v[196:199], v[120:123]
	v_mfma_f32_16x16x32_bf16 v[116:119], v[188:191], v[196:199], v[116:119]
	v_mfma_f32_16x16x32_bf16 v[104:107], v[180:183], v[204:207], v[104:107]
	v_mfma_f32_16x16x32_bf16 v[100:103], v[188:191], v[204:207], v[100:103]
	v_mfma_f32_16x16x32_bf16 v[88:91], v[180:183], v[212:215], v[88:91]
	v_mfma_f32_16x16x32_bf16 v[84:87], v[188:191], v[212:215], v[84:87]
	v_mfma_f32_16x16x32_bf16 v[72:75], v[180:183], v[220:223], v[72:75]
	v_mfma_f32_16x16x32_bf16 v[68:71], v[188:191], v[220:223], v[68:71]
	v_mfma_f32_16x16x32_bf16 v[120:123], v[184:187], v[200:203], v[120:123]
	v_mfma_f32_16x16x32_bf16 v[116:119], v[192:195], v[200:203], v[116:119]
	v_mfma_f32_16x16x32_bf16 v[104:107], v[184:187], v[208:211], v[104:107]
	v_mfma_f32_16x16x32_bf16 v[100:103], v[192:195], v[208:211], v[100:103]
	v_mfma_f32_16x16x32_bf16 v[88:91], v[184:187], v[216:219], v[88:91]
	v_mfma_f32_16x16x32_bf16 v[84:87], v[192:195], v[216:219], v[84:87]
	v_mfma_f32_16x16x32_bf16 v[72:75], v[184:187], v[224:227], v[72:75]
	v_mfma_f32_16x16x32_bf16 v[68:71], v[192:195], v[224:227], v[68:71]
	s_setprio 0
	s_barrier
	s_add_i32 s28, s69, s49
	v_lshl_add_u64 v[174:175], s[40:41], 0, v[150:151]
	s_mov_b32 m0, s28
	ds_read_b128 v[196:199], v179 offset:16384
	ds_read_b128 v[200:203], v179 offset:17408
	ds_read_b128 v[204:207], v179 offset:18432
	ds_read_b128 v[208:211], v179 offset:19456
	ds_read_b128 v[212:215], v179 offset:20480
	ds_read_b128 v[216:219], v179 offset:21504
	ds_read_b128 v[220:223], v179 offset:22528
	ds_read_b128 v[224:227], v179 offset:23552
	global_load_lds_dwordx4 v[174:175], off
	s_add_i32 m0, s28, 0x2000
	s_add_u32 s28, s40, 0x80000
	v_lshl_add_u64 v[228:229], s[40:41], 0, v[154:155]
	s_addc_u32 s29, s41, 0
	s_add_i32 s30, s70, s49
	global_load_lds_dwordx4 v[228:229], off
	v_lshl_add_u64 v[2:3], s[28:29], 0, v[150:151]
	s_mov_b32 m0, s30
	v_lshl_add_u64 v[230:231], s[42:43], 0, v[148:149]
	global_load_lds_dwordx4 v[2:3], off
	v_lshl_add_u64 v[2:3], s[28:29], 0, v[154:155]
	s_add_i32 m0, s30, 0x2000
	v_lshl_add_u64 v[232:233], s[42:43], 0, v[152:153]
	global_load_lds_dwordx4 v[2:3], off
	s_mov_b32 m0, s50
	s_nop 0
	global_load_lds_dwordx4 v[230:231], off
	s_mov_b32 m0, s51
	s_nop 0
	global_load_lds_dwordx4 v[232:233], off
	s_waitcnt vmcnt(8)
	s_waitcnt lgkmcnt(0)
	s_setprio 1
	s_barrier
	v_mfma_f32_16x16x32_bf16 v[64:67], v[132:135], v[196:199], v[64:67]
	v_mfma_f32_16x16x32_bf16 v[60:63], v[140:143], v[196:199], v[60:63]
	v_mfma_f32_16x16x32_bf16 v[48:51], v[132:135], v[204:207], v[48:51]
	v_mfma_f32_16x16x32_bf16 v[44:47], v[140:143], v[204:207], v[44:47]
	v_mfma_f32_16x16x32_bf16 v[32:35], v[132:135], v[212:215], v[32:35]
	v_mfma_f32_16x16x32_bf16 v[28:31], v[140:143], v[212:215], v[28:31]
	v_mfma_f32_16x16x32_bf16 v[16:19], v[132:135], v[220:223], v[16:19]
	v_mfma_f32_16x16x32_bf16 v[12:15], v[140:143], v[220:223], v[12:15]
	v_mfma_f32_16x16x32_bf16 v[64:67], v[136:139], v[200:203], v[64:67]
	v_mfma_f32_16x16x32_bf16 v[60:63], v[144:147], v[200:203], v[60:63]
	v_mfma_f32_16x16x32_bf16 v[48:51], v[136:139], v[208:211], v[48:51]
	v_mfma_f32_16x16x32_bf16 v[44:47], v[144:147], v[208:211], v[44:47]
	v_mfma_f32_16x16x32_bf16 v[32:35], v[136:139], v[216:219], v[32:35]
	v_mfma_f32_16x16x32_bf16 v[28:31], v[144:147], v[216:219], v[28:31]
	v_mfma_f32_16x16x32_bf16 v[16:19], v[136:139], v[224:227], v[16:19]
	v_mfma_f32_16x16x32_bf16 v[12:15], v[144:147], v[224:227], v[12:15]
	s_setprio 0
	s_setprio 1
	v_mfma_f32_16x16x32_bf16 v[56:59], v[180:183], v[196:199], v[56:59]
	v_mfma_f32_16x16x32_bf16 v[52:55], v[188:191], v[196:199], v[52:55]
	v_mfma_f32_16x16x32_bf16 v[40:43], v[180:183], v[204:207], v[40:43]
	v_mfma_f32_16x16x32_bf16 v[36:39], v[188:191], v[204:207], v[36:39]
	v_mfma_f32_16x16x32_bf16 v[24:27], v[180:183], v[212:215], v[24:27]
	v_mfma_f32_16x16x32_bf16 v[20:23], v[188:191], v[212:215], v[20:23]
	v_mfma_f32_16x16x32_bf16 v[8:11], v[180:183], v[220:223], v[8:11]
	v_mfma_f32_16x16x32_bf16 v[2:5], v[188:191], v[220:223], v[4:7]
	v_mfma_f32_16x16x32_bf16 v[56:59], v[184:187], v[200:203], v[56:59]
	v_mfma_f32_16x16x32_bf16 v[52:55], v[192:195], v[200:203], v[52:55]
	v_mfma_f32_16x16x32_bf16 v[40:43], v[184:187], v[208:211], v[40:43]
	v_mfma_f32_16x16x32_bf16 v[36:39], v[192:195], v[208:211], v[36:39]
	v_mfma_f32_16x16x32_bf16 v[24:27], v[184:187], v[216:219], v[24:27]
	v_mfma_f32_16x16x32_bf16 v[20:23], v[192:195], v[216:219], v[20:23]
	v_mfma_f32_16x16x32_bf16 v[8:11], v[184:187], v[224:227], v[8:11]
	v_mfma_f32_16x16x32_bf16 v[2:5], v[192:195], v[224:227], v[2:5]
	s_setprio 0
	s_barrier
	s_add_i32 s30, 0, 0x18000
	v_add_u32_e32 v1, s30, v177
	s_add_i32 s31, 0, 0x1c000
	ds_read_b128 v[132:135], v1
	ds_read_b128 v[136:139], v1 offset:1024
	ds_read_b128 v[140:143], v1 offset:2048
	ds_read_b128 v[144:147], v1 offset:3072
	v_add_u32_e32 v1, s31, v177
	ds_read_b128 v[180:183], v1
	ds_read_b128 v[184:187], v1 offset:1024
	ds_read_b128 v[188:191], v1 offset:2048
	ds_read_b128 v[192:195], v1 offset:3072
	s_add_u32 s28, s42, 0x80000
	s_addc_u32 s29, s43, 0
	s_mov_b32 m0, s62
	v_lshl_add_u64 v[6:7], s[28:29], 0, v[148:149]
	ds_read_b128 v[196:199], v179 offset:32768
	ds_read_b128 v[200:203], v179 offset:33792
	ds_read_b128 v[204:207], v179 offset:34816
	ds_read_b128 v[208:211], v179 offset:35840
	ds_read_b128 v[212:215], v179 offset:36864
	ds_read_b128 v[216:219], v179 offset:37888
	ds_read_b128 v[220:223], v179 offset:38912
	ds_read_b128 v[224:227], v179 offset:39936
	global_load_lds_dwordx4 v[6:7], off
	v_lshl_add_u64 v[6:7], s[28:29], 0, v[152:153]
	s_mov_b32 m0, s63
	s_nop 0
	global_load_lds_dwordx4 v[6:7], off
	s_waitcnt vmcnt(8)
	s_waitcnt lgkmcnt(0)
	s_setprio 1
	s_barrier
	v_mfma_f32_16x16x32_bf16 v[128:131], v[132:135], v[196:199], v[128:131]
	v_mfma_f32_16x16x32_bf16 v[124:127], v[140:143], v[196:199], v[124:127]
	v_mfma_f32_16x16x32_bf16 v[112:115], v[132:135], v[204:207], v[112:115]
	v_mfma_f32_16x16x32_bf16 v[108:111], v[140:143], v[204:207], v[108:111]
	v_mfma_f32_16x16x32_bf16 v[96:99], v[132:135], v[212:215], v[96:99]
	v_mfma_f32_16x16x32_bf16 v[92:95], v[140:143], v[212:215], v[92:95]
	v_mfma_f32_16x16x32_bf16 v[80:83], v[132:135], v[220:223], v[80:83]
	v_mfma_f32_16x16x32_bf16 v[76:79], v[140:143], v[220:223], v[76:79]
	v_mfma_f32_16x16x32_bf16 v[128:131], v[136:139], v[200:203], v[128:131]
	v_mfma_f32_16x16x32_bf16 v[124:127], v[144:147], v[200:203], v[124:127]
	v_mfma_f32_16x16x32_bf16 v[112:115], v[136:139], v[208:211], v[112:115]
	v_mfma_f32_16x16x32_bf16 v[108:111], v[144:147], v[208:211], v[108:111]
	v_mfma_f32_16x16x32_bf16 v[96:99], v[136:139], v[216:219], v[96:99]
	v_mfma_f32_16x16x32_bf16 v[92:95], v[144:147], v[216:219], v[92:95]
	v_mfma_f32_16x16x32_bf16 v[80:83], v[136:139], v[224:227], v[80:83]
	v_mfma_f32_16x16x32_bf16 v[76:79], v[144:147], v[224:227], v[76:79]
	s_setprio 0
	s_setprio 1
	v_mfma_f32_16x16x32_bf16 v[120:123], v[180:183], v[196:199], v[120:123]
	v_mfma_f32_16x16x32_bf16 v[116:119], v[188:191], v[196:199], v[116:119]
	v_mfma_f32_16x16x32_bf16 v[104:107], v[180:183], v[204:207], v[104:107]
	v_mfma_f32_16x16x32_bf16 v[100:103], v[188:191], v[204:207], v[100:103]
	v_mfma_f32_16x16x32_bf16 v[88:91], v[180:183], v[212:215], v[88:91]
	v_mfma_f32_16x16x32_bf16 v[84:87], v[188:191], v[212:215], v[84:87]
	v_mfma_f32_16x16x32_bf16 v[72:75], v[180:183], v[220:223], v[72:75]
	v_mfma_f32_16x16x32_bf16 v[68:71], v[188:191], v[220:223], v[68:71]
	v_mfma_f32_16x16x32_bf16 v[120:123], v[184:187], v[200:203], v[120:123]
	v_mfma_f32_16x16x32_bf16 v[116:119], v[192:195], v[200:203], v[116:119]
	v_mfma_f32_16x16x32_bf16 v[104:107], v[184:187], v[208:211], v[104:107]
	v_mfma_f32_16x16x32_bf16 v[100:103], v[192:195], v[208:211], v[100:103]
	v_mfma_f32_16x16x32_bf16 v[88:91], v[184:187], v[216:219], v[88:91]
	v_mfma_f32_16x16x32_bf16 v[84:87], v[192:195], v[216:219], v[84:87]
	v_mfma_f32_16x16x32_bf16 v[72:75], v[184:187], v[224:227], v[72:75]
	v_mfma_f32_16x16x32_bf16 v[68:71], v[192:195], v[224:227], v[68:71]
	s_setprio 0
	s_barrier
	s_add_i32 s28, s30, s49
	v_lshl_add_u64 v[6:7], v[174:175], 0, s[12:13]
	s_mov_b32 m0, s28
	ds_read_b128 v[196:199], v179 offset:49152
	ds_read_b128 v[200:203], v179 offset:50176
	ds_read_b128 v[204:207], v179 offset:51200
	ds_read_b128 v[208:211], v179 offset:52224
	ds_read_b128 v[212:215], v179 offset:53248
	ds_read_b128 v[216:219], v179 offset:54272
	ds_read_b128 v[220:223], v179 offset:55296
	ds_read_b128 v[224:227], v179 offset:56320
	global_load_lds_dwordx4 v[6:7], off
	s_add_i32 m0, s28, 0x2000
	s_add_u32 s28, s40, 0x80080
	v_lshl_add_u64 v[6:7], v[228:229], 0, s[12:13]
	s_addc_u32 s29, s41, 0
	s_add_i32 s30, s31, s49
	global_load_lds_dwordx4 v[6:7], off
	v_lshl_add_u64 v[6:7], s[28:29], 0, v[150:151]
	s_mov_b32 m0, s30
	s_nop 0
	global_load_lds_dwordx4 v[6:7], off
	v_lshl_add_u64 v[6:7], s[28:29], 0, v[154:155]
	s_add_i32 m0, s30, 0x2000
	s_nop 0
	global_load_lds_dwordx4 v[6:7], off
	v_lshl_add_u64 v[6:7], v[230:231], 0, s[12:13]
	s_mov_b32 m0, s65
	s_nop 0
	global_load_lds_dwordx4 v[6:7], off
	v_lshl_add_u64 v[6:7], v[232:233], 0, s[12:13]
	s_mov_b32 m0, s66
	s_nop 0
	global_load_lds_dwordx4 v[6:7], off
	s_waitcnt vmcnt(8)
	s_waitcnt lgkmcnt(0)
	s_setprio 1
	s_barrier
	v_mfma_f32_16x16x32_bf16 v[64:67], v[132:135], v[196:199], v[64:67]
	v_mfma_f32_16x16x32_bf16 v[60:63], v[140:143], v[196:199], v[60:63]
	v_mfma_f32_16x16x32_bf16 v[48:51], v[132:135], v[204:207], v[48:51]
	v_mfma_f32_16x16x32_bf16 v[44:47], v[140:143], v[204:207], v[44:47]
	v_mfma_f32_16x16x32_bf16 v[32:35], v[132:135], v[212:215], v[32:35]
	v_mfma_f32_16x16x32_bf16 v[28:31], v[140:143], v[212:215], v[28:31]
	v_mfma_f32_16x16x32_bf16 v[16:19], v[132:135], v[220:223], v[16:19]
	v_mfma_f32_16x16x32_bf16 v[12:15], v[140:143], v[220:223], v[12:15]
	v_mfma_f32_16x16x32_bf16 v[64:67], v[136:139], v[200:203], v[64:67]
	v_mfma_f32_16x16x32_bf16 v[60:63], v[144:147], v[200:203], v[60:63]
	v_mfma_f32_16x16x32_bf16 v[48:51], v[136:139], v[208:211], v[48:51]
	v_mfma_f32_16x16x32_bf16 v[44:47], v[144:147], v[208:211], v[44:47]
	v_mfma_f32_16x16x32_bf16 v[32:35], v[136:139], v[216:219], v[32:35]
	v_mfma_f32_16x16x32_bf16 v[28:31], v[144:147], v[216:219], v[28:31]
	v_mfma_f32_16x16x32_bf16 v[16:19], v[136:139], v[224:227], v[16:19]
	v_mfma_f32_16x16x32_bf16 v[12:15], v[144:147], v[224:227], v[12:15]
	s_setprio 0
	s_setprio 1
	v_mfma_f32_16x16x32_bf16 v[56:59], v[180:183], v[196:199], v[56:59]
	v_mfma_f32_16x16x32_bf16 v[52:55], v[188:191], v[196:199], v[52:55]
	v_mfma_f32_16x16x32_bf16 v[40:43], v[180:183], v[204:207], v[40:43]
	v_mfma_f32_16x16x32_bf16 v[36:39], v[188:191], v[204:207], v[36:39]
	v_mfma_f32_16x16x32_bf16 v[24:27], v[180:183], v[212:215], v[24:27]
	v_mfma_f32_16x16x32_bf16 v[20:23], v[188:191], v[212:215], v[20:23]
	v_mfma_f32_16x16x32_bf16 v[6:9], v[180:183], v[220:223], v[8:11]
	v_mfma_f32_16x16x32_bf16 v[2:5], v[188:191], v[220:223], v[2:5]
	v_mfma_f32_16x16x32_bf16 v[56:59], v[184:187], v[200:203], v[56:59]
	v_mfma_f32_16x16x32_bf16 v[52:55], v[192:195], v[200:203], v[52:55]
	v_mfma_f32_16x16x32_bf16 v[40:43], v[184:187], v[208:211], v[40:43]
	v_mfma_f32_16x16x32_bf16 v[36:39], v[192:195], v[208:211], v[36:39]
	v_mfma_f32_16x16x32_bf16 v[24:27], v[184:187], v[216:219], v[24:27]
	v_mfma_f32_16x16x32_bf16 v[20:23], v[192:195], v[216:219], v[20:23]
	v_mfma_f32_16x16x32_bf16 v[8:11], v[184:187], v[224:227], v[6:9]
	v_mfma_f32_16x16x32_bf16 v[4:7], v[192:195], v[224:227], v[2:5]
	s_setprio 0
	s_barrier
	s_add_i32 s75, s75, 2
	s_add_u32 s38, s38, 0x100
	s_addc_u32 s39, s39, 0
	s_cmp_gt_u32 s75, 29
	s_cbranch_scc1 .LBB0_659

.LBB0_738:
	ds_read_b128 v[16:19], v189
	ds_read_b128 v[20:23], v189 offset:1024
	ds_read_b128 v[24:27], v189 offset:2048
	ds_read_b128 v[28:31], v189 offset:3072
	ds_read_b128 v[0:3], v190
	ds_read_b128 v[4:7], v190 offset:1024
	ds_read_b128 v[8:11], v190 offset:2048
	ds_read_b128 v[12:15], v190 offset:3072
	s_add_u32 s28, s62, 0xfffc0080
	s_addc_u32 s29, s63, -1
	s_cmp_eq_u32 s87, 12
	s_cselect_b32 s67, s47, s29
	s_cselect_b32 s66, s83, s28
	s_cselect_b32 s65, s45, s86
	s_cselect_b32 s64, s84, s85
	v_lshl_add_u64 v[218:219], s[62:63], 0, v[170:171]
	s_add_i32 m0, s61, 0xc000
	ds_read_b128 v[178:181], v191
	ds_read_b128 v[182:185], v191 offset:1024
	ds_read_b128 v[194:197], v191 offset:2048
	ds_read_b128 v[198:201], v191 offset:3072
	ds_read_b128 v[202:205], v191 offset:4096
	ds_read_b128 v[206:209], v191 offset:5120
	ds_read_b128 v[210:213], v191 offset:6144
	ds_read_b128 v[214:217], v191 offset:7168
	global_load_lds_dwordx4 v[218:219], off
	v_lshl_add_u64 v[218:219], s[62:63], 0, v[172:173]
	s_add_i32 m0, s61, 0xe000
	s_nop 0
	global_load_lds_dwordx4 v[218:219], off
	s_waitcnt vmcnt(8)
	s_waitcnt lgkmcnt(0)
	s_setprio 1
	s_barrier
	v_mfma_scale_f32_16x16x128_f8f6f4 v[156:159], v[16:23], v[178:185], v[156:159], v192, v192 op_sel_hi:[0,0,0]
	v_mfma_scale_f32_16x16x128_f8f6f4 v[152:155], v[24:31], v[178:185], v[152:155], v192, v192 op_sel_hi:[0,0,0]
	v_mfma_scale_f32_16x16x128_f8f6f4 v[148:151], v[16:23], v[194:201], v[148:151], v192, v192 op_sel_hi:[0,0,0]
	v_mfma_scale_f32_16x16x128_f8f6f4 v[144:147], v[24:31], v[194:201], v[144:147], v192, v192 op_sel_hi:[0,0,0]
	v_mfma_scale_f32_16x16x128_f8f6f4 v[140:143], v[16:23], v[202:209], v[140:143], v192, v192 op_sel_hi:[0,0,0]
	v_mfma_scale_f32_16x16x128_f8f6f4 v[136:139], v[24:31], v[202:209], v[136:139], v192, v192 op_sel_hi:[0,0,0]
	v_mfma_scale_f32_16x16x128_f8f6f4 v[132:135], v[16:23], v[210:217], v[132:135], v192, v192 op_sel_hi:[0,0,0]
	v_mfma_scale_f32_16x16x128_f8f6f4 v[128:131], v[24:31], v[210:217], v[128:131], v192, v192 op_sel_hi:[0,0,0]
	s_setprio 0
	s_setprio 1
	v_mfma_scale_f32_16x16x128_f8f6f4 v[100:103], v[0:7], v[178:185], v[100:103], v192, v192 op_sel_hi:[0,0,0]
	v_mfma_scale_f32_16x16x128_f8f6f4 v[96:99], v[8:15], v[178:185], v[96:99], v192, v192 op_sel_hi:[0,0,0]
	v_mfma_scale_f32_16x16x128_f8f6f4 v[84:87], v[0:7], v[194:201], v[84:87], v192, v192 op_sel_hi:[0,0,0]
	v_mfma_scale_f32_16x16x128_f8f6f4 v[80:83], v[8:15], v[194:201], v[80:83], v192, v192 op_sel_hi:[0,0,0]
	v_mfma_scale_f32_16x16x128_f8f6f4 v[76:79], v[0:7], v[202:209], v[76:79], v192, v192 op_sel_hi:[0,0,0]
	v_mfma_scale_f32_16x16x128_f8f6f4 v[72:75], v[8:15], v[202:209], v[72:75], v192, v192 op_sel_hi:[0,0,0]
	v_mfma_scale_f32_16x16x128_f8f6f4 v[68:71], v[0:7], v[210:217], v[68:71], v192, v192 op_sel_hi:[0,0,0]
	v_mfma_scale_f32_16x16x128_f8f6f4 v[64:67], v[8:15], v[210:217], v[64:67], v192, v192 op_sel_hi:[0,0,0]
	s_setprio 0
	s_barrier
	s_add_i32 s28, s80, s23
	v_lshl_add_u64 v[178:179], s[64:65], 0, v[162:163]
	s_mov_b32 m0, s28
	ds_read_b128 v[194:197], v191 offset:16384
	ds_read_b128 v[198:201], v191 offset:17408
	ds_read_b128 v[202:205], v191 offset:18432
	ds_read_b128 v[206:209], v191 offset:19456
	ds_read_b128 v[210:213], v191 offset:20480
	ds_read_b128 v[214:217], v191 offset:21504
	ds_read_b128 v[218:221], v191 offset:22528
	ds_read_b128 v[222:225], v191 offset:23552
	global_load_lds_dwordx4 v[178:179], off
	s_add_i32 m0, s28, 0x2000
	s_add_u32 s28, s64, 0x40000
	v_lshl_add_u64 v[180:181], s[64:65], 0, v[166:167]
	s_addc_u32 s29, s65, 0
	s_add_i32 s30, s81, s23
	global_load_lds_dwordx4 v[180:181], off
	v_lshl_add_u64 v[182:183], s[28:29], 0, v[162:163]
	s_mov_b32 m0, s30
	v_lshl_add_u64 v[184:185], s[66:67], 0, v[164:165]
	global_load_lds_dwordx4 v[182:183], off
	v_lshl_add_u64 v[182:183], s[28:29], 0, v[166:167]
	s_add_i32 m0, s30, 0x2000
	s_nop 0
	global_load_lds_dwordx4 v[182:183], off
	v_lshl_add_u64 v[182:183], s[66:67], 0, v[160:161]
	s_mov_b32 m0, s61
	s_nop 0
	global_load_lds_dwordx4 v[182:183], off
	s_mov_b32 m0, s72
	s_nop 0
	global_load_lds_dwordx4 v[184:185], off
	s_waitcnt vmcnt(8)
	s_waitcnt lgkmcnt(0)
	s_setprio 1
	s_barrier
	v_mfma_scale_f32_16x16x128_f8f6f4 v[124:127], v[16:23], v[194:201], v[124:127], v192, v192 op_sel_hi:[0,0,0]
	v_mfma_scale_f32_16x16x128_f8f6f4 v[120:123], v[24:31], v[194:201], v[120:123], v192, v192 op_sel_hi:[0,0,0]
	v_mfma_scale_f32_16x16x128_f8f6f4 v[116:119], v[16:23], v[202:209], v[116:119], v192, v192 op_sel_hi:[0,0,0]
	v_mfma_scale_f32_16x16x128_f8f6f4 v[112:115], v[24:31], v[202:209], v[112:115], v192, v192 op_sel_hi:[0,0,0]
	v_mfma_scale_f32_16x16x128_f8f6f4 v[108:111], v[16:23], v[210:217], v[108:111], v192, v192 op_sel_hi:[0,0,0]
	v_mfma_scale_f32_16x16x128_f8f6f4 v[104:107], v[24:31], v[210:217], v[104:107], v192, v192 op_sel_hi:[0,0,0]
	v_mfma_scale_f32_16x16x128_f8f6f4 v[92:95], v[16:23], v[218:225], v[92:95], v192, v192 op_sel_hi:[0,0,0]
	v_mfma_scale_f32_16x16x128_f8f6f4 v[88:91], v[24:31], v[218:225], v[88:91], v192, v192 op_sel_hi:[0,0,0]
	s_setprio 0
	s_setprio 1
	v_mfma_scale_f32_16x16x128_f8f6f4 v[60:63], v[0:7], v[194:201], v[60:63], v192, v192 op_sel_hi:[0,0,0]
	v_mfma_scale_f32_16x16x128_f8f6f4 v[56:59], v[8:15], v[194:201], v[56:59], v192, v192 op_sel_hi:[0,0,0]
	v_mfma_scale_f32_16x16x128_f8f6f4 v[52:55], v[0:7], v[202:209], v[52:55], v192, v192 op_sel_hi:[0,0,0]
	v_mfma_scale_f32_16x16x128_f8f6f4 v[48:51], v[8:15], v[202:209], v[48:51], v192, v192 op_sel_hi:[0,0,0]
	v_mfma_scale_f32_16x16x128_f8f6f4 v[44:47], v[0:7], v[210:217], v[44:47], v192, v192 op_sel_hi:[0,0,0]
	v_mfma_scale_f32_16x16x128_f8f6f4 v[40:43], v[8:15], v[210:217], v[40:43], v192, v192 op_sel_hi:[0,0,0]
	v_mfma_scale_f32_16x16x128_f8f6f4 v[36:39], v[0:7], v[218:225], v[36:39], v192, v192 op_sel_hi:[0,0,0]
	v_mfma_scale_f32_16x16x128_f8f6f4 v[32:35], v[8:15], v[218:225], v[32:35], v192, v192 op_sel_hi:[0,0,0]
	s_setprio 0
	s_barrier
	s_add_i32 s30, 0, 0x18000
	s_add_i32 s31, 0, 0x1c000
	v_add_u32_e32 v12, s30, v187
	v_add_u32_e32 v28, s31, v187
	ds_read_b128 v[0:3], v12
	ds_read_b128 v[4:7], v12 offset:1024
	ds_read_b128 v[8:11], v12 offset:2048
	ds_read_b128 v[12:15], v12 offset:3072
	ds_read_b128 v[16:19], v28
	ds_read_b128 v[20:23], v28 offset:1024
	ds_read_b128 v[24:27], v28 offset:2048
	ds_read_b128 v[28:31], v28 offset:3072
	s_add_u32 s28, s66, 0x40000
	s_addc_u32 s29, s67, 0
	s_mov_b32 m0, s73
	v_lshl_add_u64 v[226:227], s[28:29], 0, v[160:161]
	ds_read_b128 v[194:197], v191 offset:32768
	ds_read_b128 v[198:201], v191 offset:33792
	ds_read_b128 v[202:205], v191 offset:34816
	ds_read_b128 v[206:209], v191 offset:35840
	ds_read_b128 v[210:213], v191 offset:36864
	ds_read_b128 v[214:217], v191 offset:37888
	ds_read_b128 v[218:221], v191 offset:38912
	ds_read_b128 v[222:225], v191 offset:39936
	global_load_lds_dwordx4 v[226:227], off
	v_lshl_add_u64 v[226:227], s[28:29], 0, v[164:165]
	s_mov_b32 m0, s74
	s_nop 0
	global_load_lds_dwordx4 v[226:227], off
	s_waitcnt vmcnt(8)
	s_waitcnt lgkmcnt(0)
	s_setprio 1
	s_barrier
	v_mfma_scale_f32_16x16x128_f8f6f4 v[156:159], v[0:7], v[194:201], v[156:159], v192, v192 op_sel_hi:[0,0,0]
	v_mfma_scale_f32_16x16x128_f8f6f4 v[152:155], v[8:15], v[194:201], v[152:155], v192, v192 op_sel_hi:[0,0,0]
	v_mfma_scale_f32_16x16x128_f8f6f4 v[148:151], v[0:7], v[202:209], v[148:151], v192, v192 op_sel_hi:[0,0,0]
	v_mfma_scale_f32_16x16x128_f8f6f4 v[144:147], v[8:15], v[202:209], v[144:147], v192, v192 op_sel_hi:[0,0,0]
	v_mfma_scale_f32_16x16x128_f8f6f4 v[140:143], v[0:7], v[210:217], v[140:143], v192, v192 op_sel_hi:[0,0,0]
	v_mfma_scale_f32_16x16x128_f8f6f4 v[136:139], v[8:15], v[210:217], v[136:139], v192, v192 op_sel_hi:[0,0,0]
	v_mfma_scale_f32_16x16x128_f8f6f4 v[132:135], v[0:7], v[218:225], v[132:135], v192, v192 op_sel_hi:[0,0,0]
	v_mfma_scale_f32_16x16x128_f8f6f4 v[128:131], v[8:15], v[218:225], v[128:131], v192, v192 op_sel_hi:[0,0,0]
	s_setprio 0
	s_setprio 1
	v_mfma_scale_f32_16x16x128_f8f6f4 v[100:103], v[16:23], v[194:201], v[100:103], v192, v192 op_sel_hi:[0,0,0]
	v_mfma_scale_f32_16x16x128_f8f6f4 v[96:99], v[24:31], v[194:201], v[96:99], v192, v192 op_sel_hi:[0,0,0]
	v_mfma_scale_f32_16x16x128_f8f6f4 v[84:87], v[16:23], v[202:209], v[84:87], v192, v192 op_sel_hi:[0,0,0]
	v_mfma_scale_f32_16x16x128_f8f6f4 v[80:83], v[24:31], v[202:209], v[80:83], v192, v192 op_sel_hi:[0,0,0]
	v_mfma_scale_f32_16x16x128_f8f6f4 v[76:79], v[16:23], v[210:217], v[76:79], v192, v192 op_sel_hi:[0,0,0]
	v_mfma_scale_f32_16x16x128_f8f6f4 v[72:75], v[24:31], v[210:217], v[72:75], v192, v192 op_sel_hi:[0,0,0]
	v_mfma_scale_f32_16x16x128_f8f6f4 v[68:71], v[16:23], v[218:225], v[68:71], v192, v192 op_sel_hi:[0,0,0]
	v_mfma_scale_f32_16x16x128_f8f6f4 v[64:67], v[24:31], v[218:225], v[64:67], v192, v192 op_sel_hi:[0,0,0]
	s_setprio 0
	s_barrier
	s_add_i32 s28, s30, s23
	v_lshl_add_u64 v[178:179], v[178:179], 0, s[12:13]
	s_mov_b32 m0, s28
	ds_read_b128 v[194:197], v191 offset:49152
	ds_read_b128 v[198:201], v191 offset:50176
	ds_read_b128 v[202:205], v191 offset:51200
	ds_read_b128 v[206:209], v191 offset:52224
	ds_read_b128 v[210:213], v191 offset:53248
	ds_read_b128 v[214:217], v191 offset:54272
	ds_read_b128 v[218:221], v191 offset:55296
	ds_read_b128 v[222:225], v191 offset:56320
	global_load_lds_dwordx4 v[178:179], off
	s_add_i32 m0, s28, 0x2000
	s_add_u32 s28, s64, 0x40080
	v_lshl_add_u64 v[178:179], v[180:181], 0, s[12:13]
	s_addc_u32 s29, s65, 0
	s_add_i32 s30, s31, s23
	global_load_lds_dwordx4 v[178:179], off
	v_lshl_add_u64 v[178:179], s[28:29], 0, v[162:163]
	s_mov_b32 m0, s30
	s_nop 0
	global_load_lds_dwordx4 v[178:179], off
	v_lshl_add_u64 v[178:179], s[28:29], 0, v[166:167]
	s_add_i32 m0, s30, 0x2000
	s_nop 0
	global_load_lds_dwordx4 v[178:179], off
	v_lshl_add_u64 v[178:179], v[182:183], 0, s[12:13]
	s_mov_b32 m0, s76
	s_nop 0
	global_load_lds_dwordx4 v[178:179], off
	v_lshl_add_u64 v[178:179], v[184:185], 0, s[12:13]
	s_mov_b32 m0, s77
	s_nop 0
	global_load_lds_dwordx4 v[178:179], off
	s_waitcnt vmcnt(8)
	s_waitcnt lgkmcnt(0)
	s_setprio 1
	s_barrier
	v_mfma_scale_f32_16x16x128_f8f6f4 v[124:127], v[0:7], v[194:201], v[124:127], v192, v192 op_sel_hi:[0,0,0]
	v_mfma_scale_f32_16x16x128_f8f6f4 v[120:123], v[8:15], v[194:201], v[120:123], v192, v192 op_sel_hi:[0,0,0]
	v_mfma_scale_f32_16x16x128_f8f6f4 v[116:119], v[0:7], v[202:209], v[116:119], v192, v192 op_sel_hi:[0,0,0]
	v_mfma_scale_f32_16x16x128_f8f6f4 v[112:115], v[8:15], v[202:209], v[112:115], v192, v192 op_sel_hi:[0,0,0]
	v_mfma_scale_f32_16x16x128_f8f6f4 v[108:111], v[0:7], v[210:217], v[108:111], v192, v192 op_sel_hi:[0,0,0]
	v_mfma_scale_f32_16x16x128_f8f6f4 v[104:107], v[8:15], v[210:217], v[104:107], v192, v192 op_sel_hi:[0,0,0]
	v_mfma_scale_f32_16x16x128_f8f6f4 v[92:95], v[0:7], v[218:225], v[92:95], v192, v192 op_sel_hi:[0,0,0]
	v_mfma_scale_f32_16x16x128_f8f6f4 v[88:91], v[8:15], v[218:225], v[88:91], v192, v192 op_sel_hi:[0,0,0]
	s_setprio 0
	s_setprio 1
	v_mfma_scale_f32_16x16x128_f8f6f4 v[60:63], v[16:23], v[194:201], v[60:63], v192, v192 op_sel_hi:[0,0,0]
	v_mfma_scale_f32_16x16x128_f8f6f4 v[56:59], v[24:31], v[194:201], v[56:59], v192, v192 op_sel_hi:[0,0,0]
	v_mfma_scale_f32_16x16x128_f8f6f4 v[52:55], v[16:23], v[202:209], v[52:55], v192, v192 op_sel_hi:[0,0,0]
	v_mfma_scale_f32_16x16x128_f8f6f4 v[48:51], v[24:31], v[202:209], v[48:51], v192, v192 op_sel_hi:[0,0,0]
	v_mfma_scale_f32_16x16x128_f8f6f4 v[44:47], v[16:23], v[210:217], v[44:47], v192, v192 op_sel_hi:[0,0,0]
	v_mfma_scale_f32_16x16x128_f8f6f4 v[40:43], v[24:31], v[210:217], v[40:43], v192, v192 op_sel_hi:[0,0,0]
	v_mfma_scale_f32_16x16x128_f8f6f4 v[36:39], v[16:23], v[218:225], v[36:39], v192, v192 op_sel_hi:[0,0,0]
	v_mfma_scale_f32_16x16x128_f8f6f4 v[32:35], v[24:31], v[218:225], v[32:35], v192, v192 op_sel_hi:[0,0,0]
	s_setprio 0
	s_barrier
	s_add_i32 s87, s87, 2
	s_add_u32 s62, s62, 0x100
	s_addc_u32 s63, s63, 0
	s_add_u32 s85, s85, 0x100
	s_addc_u32 s86, s86, 0
	s_cmp_gt_u32 s87, 13
	s_cbranch_scc0 .LBB0_738
	s_and_b64 vcc, exec, s[14:15]
	s_cbranch_vccz .LBB0_741
	s_barrier

.LBB0_818:
	v_add_u32_e32 v0, s51, v193
	v_add_u32_e32 v12, s58, v193
	s_add_u32 s28, s12, s26
	ds_read_b128 v[16:19], v0
	ds_read_b128 v[20:23], v0 offset:1024
	ds_read_b128 v[24:27], v0 offset:2048
	ds_read_b128 v[28:31], v0 offset:3072
	ds_read_b128 v[0:3], v12
	ds_read_b128 v[4:7], v12 offset:1024
	ds_read_b128 v[8:11], v12 offset:2048
	ds_read_b128 v[12:15], v12 offset:3072
	s_addc_u32 s29, s13, s27
	s_add_u32 s28, s28, 0x100
	s_addc_u32 s29, s29, 0
	s_add_u32 s30, s23, s26
	s_addc_u32 s31, s59, s27
	s_cmpk_eq_i32 s26, 0x700
	s_cselect_b32 s41, s19, s29
	s_cselect_b32 s40, s60, s28
	s_cselect_b32 s39, s17, s31
	s_cselect_b32 s38, s61, s30
	v_lshl_add_u64 v[220:221], v[178:179], 0, s[26:27]
	s_add_i32 m0, s43, 0xc000
	ds_read_b128 v[182:185], v194
	ds_read_b128 v[186:189], v194 offset:1024
	ds_read_b128 v[196:199], v194 offset:2048
	ds_read_b128 v[200:203], v194 offset:3072
	ds_read_b128 v[204:207], v194 offset:4096
	ds_read_b128 v[208:211], v194 offset:5120
	ds_read_b128 v[212:215], v194 offset:6144
	ds_read_b128 v[216:219], v194 offset:7168
	global_load_lds_dwordx4 v[220:221], off
	v_lshl_add_u64 v[220:221], v[180:181], 0, s[26:27]
	s_add_i32 m0, s43, 0xe000
	s_nop 0
	global_load_lds_dwordx4 v[220:221], off
	s_waitcnt vmcnt(8)
	s_waitcnt lgkmcnt(0)
	s_setprio 1
	s_barrier
	v_mfma_scale_f32_16x16x128_f8f6f4 v[156:159], v[16:23], v[182:189], v[156:159], v195, v195 op_sel_hi:[0,0,0]
	v_mfma_scale_f32_16x16x128_f8f6f4 v[152:155], v[24:31], v[182:189], v[152:155], v195, v195 op_sel_hi:[0,0,0]
	v_mfma_scale_f32_16x16x128_f8f6f4 v[148:151], v[16:23], v[196:203], v[148:151], v195, v195 op_sel_hi:[0,0,0]
	v_mfma_scale_f32_16x16x128_f8f6f4 v[144:147], v[24:31], v[196:203], v[144:147], v195, v195 op_sel_hi:[0,0,0]
	v_mfma_scale_f32_16x16x128_f8f6f4 v[140:143], v[16:23], v[204:211], v[140:143], v195, v195 op_sel_hi:[0,0,0]
	v_mfma_scale_f32_16x16x128_f8f6f4 v[136:139], v[24:31], v[204:211], v[136:139], v195, v195 op_sel_hi:[0,0,0]
	v_mfma_scale_f32_16x16x128_f8f6f4 v[132:135], v[16:23], v[212:219], v[132:135], v195, v195 op_sel_hi:[0,0,0]
	v_mfma_scale_f32_16x16x128_f8f6f4 v[128:131], v[24:31], v[212:219], v[128:131], v195, v195 op_sel_hi:[0,0,0]
	s_setprio 0
	s_setprio 1
	v_mfma_scale_f32_16x16x128_f8f6f4 v[92:95], v[0:7], v[182:189], v[92:95], v195, v195 op_sel_hi:[0,0,0]
	v_mfma_scale_f32_16x16x128_f8f6f4 v[88:91], v[8:15], v[182:189], v[88:91], v195, v195 op_sel_hi:[0,0,0]
	v_mfma_scale_f32_16x16x128_f8f6f4 v[84:87], v[0:7], v[196:203], v[84:87], v195, v195 op_sel_hi:[0,0,0]
	v_mfma_scale_f32_16x16x128_f8f6f4 v[80:83], v[8:15], v[196:203], v[80:83], v195, v195 op_sel_hi:[0,0,0]
	v_mfma_scale_f32_16x16x128_f8f6f4 v[76:79], v[0:7], v[204:211], v[76:79], v195, v195 op_sel_hi:[0,0,0]
	v_mfma_scale_f32_16x16x128_f8f6f4 v[72:75], v[8:15], v[204:211], v[72:75], v195, v195 op_sel_hi:[0,0,0]
	v_mfma_scale_f32_16x16x128_f8f6f4 v[68:71], v[0:7], v[212:219], v[68:71], v195, v195 op_sel_hi:[0,0,0]
	v_mfma_scale_f32_16x16x128_f8f6f4 v[64:67], v[8:15], v[212:219], v[64:67], v195, v195 op_sel_hi:[0,0,0]
	s_setprio 0
	s_barrier
	s_add_i32 s28, s51, s42
	v_lshl_add_u64 v[182:183], s[38:39], 0, v[162:163]
	s_mov_b32 m0, s28
	ds_read_b128 v[196:199], v194 offset:16384
	ds_read_b128 v[200:203], v194 offset:17408
	ds_read_b128 v[204:207], v194 offset:18432
	ds_read_b128 v[208:211], v194 offset:19456
	ds_read_b128 v[212:215], v194 offset:20480
	ds_read_b128 v[216:219], v194 offset:21504
	ds_read_b128 v[220:223], v194 offset:22528
	ds_read_b128 v[224:227], v194 offset:23552
	global_load_lds_dwordx4 v[182:183], off
	s_add_i32 m0, s28, 0x2000
	s_add_u32 s28, s38, 0x40000
	v_lshl_add_u64 v[184:185], s[38:39], 0, v[166:167]
	s_addc_u32 s29, s39, 0
	s_add_i32 s30, s58, s42
	global_load_lds_dwordx4 v[184:185], off
	v_lshl_add_u64 v[186:187], s[28:29], 0, v[162:163]
	s_mov_b32 m0, s30
	v_lshl_add_u64 v[188:189], s[40:41], 0, v[164:165]
	global_load_lds_dwordx4 v[186:187], off
	v_lshl_add_u64 v[186:187], s[28:29], 0, v[166:167]
	s_add_i32 m0, s30, 0x2000
	s_nop 0
	global_load_lds_dwordx4 v[186:187], off
	v_lshl_add_u64 v[186:187], s[40:41], 0, v[160:161]
	s_mov_b32 m0, s43
	s_nop 0
	global_load_lds_dwordx4 v[186:187], off
	s_mov_b32 m0, s44
	s_nop 0
	global_load_lds_dwordx4 v[188:189], off
	s_waitcnt vmcnt(8)
	s_waitcnt lgkmcnt(0)
	s_setprio 1
	s_barrier
	v_mfma_scale_f32_16x16x128_f8f6f4 v[124:127], v[16:23], v[196:203], v[124:127], v195, v195 op_sel_hi:[0,0,0]
	v_mfma_scale_f32_16x16x128_f8f6f4 v[120:123], v[24:31], v[196:203], v[120:123], v195, v195 op_sel_hi:[0,0,0]
	v_mfma_scale_f32_16x16x128_f8f6f4 v[116:119], v[16:23], v[204:211], v[116:119], v195, v195 op_sel_hi:[0,0,0]
	v_mfma_scale_f32_16x16x128_f8f6f4 v[112:115], v[24:31], v[204:211], v[112:115], v195, v195 op_sel_hi:[0,0,0]
	v_mfma_scale_f32_16x16x128_f8f6f4 v[108:111], v[16:23], v[212:219], v[108:111], v195, v195 op_sel_hi:[0,0,0]
	v_mfma_scale_f32_16x16x128_f8f6f4 v[104:107], v[24:31], v[212:219], v[104:107], v195, v195 op_sel_hi:[0,0,0]
	v_mfma_scale_f32_16x16x128_f8f6f4 v[100:103], v[16:23], v[220:227], v[100:103], v195, v195 op_sel_hi:[0,0,0]
	v_mfma_scale_f32_16x16x128_f8f6f4 v[96:99], v[24:31], v[220:227], v[96:99], v195, v195 op_sel_hi:[0,0,0]
	s_setprio 0
	s_setprio 1
	v_mfma_scale_f32_16x16x128_f8f6f4 v[60:63], v[0:7], v[196:203], v[60:63], v195, v195 op_sel_hi:[0,0,0]
	v_mfma_scale_f32_16x16x128_f8f6f4 v[56:59], v[8:15], v[196:203], v[56:59], v195, v195 op_sel_hi:[0,0,0]
	v_mfma_scale_f32_16x16x128_f8f6f4 v[52:55], v[0:7], v[204:211], v[52:55], v195, v195 op_sel_hi:[0,0,0]
	v_mfma_scale_f32_16x16x128_f8f6f4 v[48:51], v[8:15], v[204:211], v[48:51], v195, v195 op_sel_hi:[0,0,0]
	v_mfma_scale_f32_16x16x128_f8f6f4 v[44:47], v[0:7], v[212:219], v[44:47], v195, v195 op_sel_hi:[0,0,0]
	v_mfma_scale_f32_16x16x128_f8f6f4 v[40:43], v[8:15], v[212:219], v[40:43], v195, v195 op_sel_hi:[0,0,0]
	v_mfma_scale_f32_16x16x128_f8f6f4 v[36:39], v[0:7], v[220:227], v[36:39], v195, v195 op_sel_hi:[0,0,0]
	v_mfma_scale_f32_16x16x128_f8f6f4 v[32:35], v[8:15], v[220:227], v[32:35], v195, v195 op_sel_hi:[0,0,0]
	s_setprio 0
	s_barrier
	s_add_i32 s30, 0, 0x18000
	s_add_i32 s31, 0, 0x1c000
	v_add_u32_e32 v12, s30, v193
	v_add_u32_e32 v28, s31, v193
	ds_read_b128 v[0:3], v12
	ds_read_b128 v[4:7], v12 offset:1024
	ds_read_b128 v[8:11], v12 offset:2048
	ds_read_b128 v[12:15], v12 offset:3072
	ds_read_b128 v[16:19], v28
	ds_read_b128 v[20:23], v28 offset:1024
	ds_read_b128 v[24:27], v28 offset:2048
	ds_read_b128 v[28:31], v28 offset:3072
	s_add_u32 s28, s40, 0x40000
	s_addc_u32 s29, s41, 0
	s_mov_b32 m0, s45
	v_lshl_add_u64 v[228:229], s[28:29], 0, v[160:161]
	ds_read_b128 v[196:199], v194 offset:32768
	ds_read_b128 v[200:203], v194 offset:33792
	ds_read_b128 v[204:207], v194 offset:34816
	ds_read_b128 v[208:211], v194 offset:35840
	ds_read_b128 v[212:215], v194 offset:36864
	ds_read_b128 v[216:219], v194 offset:37888
	ds_read_b128 v[220:223], v194 offset:38912
	ds_read_b128 v[224:227], v194 offset:39936
	global_load_lds_dwordx4 v[228:229], off
	v_lshl_add_u64 v[228:229], s[28:29], 0, v[164:165]
	s_mov_b32 m0, s46
	s_nop 0
	global_load_lds_dwordx4 v[228:229], off
	s_waitcnt vmcnt(8)
	s_waitcnt lgkmcnt(0)
	s_setprio 1
	s_barrier
	v_mfma_scale_f32_16x16x128_f8f6f4 v[156:159], v[0:7], v[196:203], v[156:159], v195, v195 op_sel_hi:[0,0,0]
	v_mfma_scale_f32_16x16x128_f8f6f4 v[152:155], v[8:15], v[196:203], v[152:155], v195, v195 op_sel_hi:[0,0,0]
	v_mfma_scale_f32_16x16x128_f8f6f4 v[148:151], v[0:7], v[204:211], v[148:151], v195, v195 op_sel_hi:[0,0,0]
	v_mfma_scale_f32_16x16x128_f8f6f4 v[144:147], v[8:15], v[204:211], v[144:147], v195, v195 op_sel_hi:[0,0,0]
	v_mfma_scale_f32_16x16x128_f8f6f4 v[140:143], v[0:7], v[212:219], v[140:143], v195, v195 op_sel_hi:[0,0,0]
	v_mfma_scale_f32_16x16x128_f8f6f4 v[136:139], v[8:15], v[212:219], v[136:139], v195, v195 op_sel_hi:[0,0,0]
	v_mfma_scale_f32_16x16x128_f8f6f4 v[132:135], v[0:7], v[220:227], v[132:135], v195, v195 op_sel_hi:[0,0,0]
	v_mfma_scale_f32_16x16x128_f8f6f4 v[128:131], v[8:15], v[220:227], v[128:131], v195, v195 op_sel_hi:[0,0,0]
	s_setprio 0
	s_setprio 1
	v_mfma_scale_f32_16x16x128_f8f6f4 v[92:95], v[16:23], v[196:203], v[92:95], v195, v195 op_sel_hi:[0,0,0]
	v_mfma_scale_f32_16x16x128_f8f6f4 v[88:91], v[24:31], v[196:203], v[88:91], v195, v195 op_sel_hi:[0,0,0]
	v_mfma_scale_f32_16x16x128_f8f6f4 v[84:87], v[16:23], v[204:211], v[84:87], v195, v195 op_sel_hi:[0,0,0]
	v_mfma_scale_f32_16x16x128_f8f6f4 v[80:83], v[24:31], v[204:211], v[80:83], v195, v195 op_sel_hi:[0,0,0]
	v_mfma_scale_f32_16x16x128_f8f6f4 v[76:79], v[16:23], v[212:219], v[76:79], v195, v195 op_sel_hi:[0,0,0]
	v_mfma_scale_f32_16x16x128_f8f6f4 v[72:75], v[24:31], v[212:219], v[72:75], v195, v195 op_sel_hi:[0,0,0]
	v_mfma_scale_f32_16x16x128_f8f6f4 v[68:71], v[16:23], v[220:227], v[68:71], v195, v195 op_sel_hi:[0,0,0]
	v_mfma_scale_f32_16x16x128_f8f6f4 v[64:67], v[24:31], v[220:227], v[64:67], v195, v195 op_sel_hi:[0,0,0]
	s_setprio 0
	s_barrier
	s_add_i32 s28, s30, s42
	v_lshl_add_u64 v[182:183], v[182:183], 0, s[14:15]
	s_mov_b32 m0, s28
	ds_read_b128 v[196:199], v194 offset:49152
	ds_read_b128 v[200:203], v194 offset:50176
	ds_read_b128 v[204:207], v194 offset:51200
	ds_read_b128 v[208:211], v194 offset:52224
	ds_read_b128 v[212:215], v194 offset:53248
	ds_read_b128 v[216:219], v194 offset:54272
	ds_read_b128 v[220:223], v194 offset:55296
	ds_read_b128 v[224:227], v194 offset:56320
	global_load_lds_dwordx4 v[182:183], off
	s_add_i32 m0, s28, 0x2000
	s_add_u32 s28, s38, 0x40080
	v_lshl_add_u64 v[182:183], v[184:185], 0, s[14:15]
	s_addc_u32 s29, s39, 0
	s_add_i32 s30, s31, s42
	global_load_lds_dwordx4 v[182:183], off
	v_lshl_add_u64 v[182:183], s[28:29], 0, v[162:163]
	s_mov_b32 m0, s30
	s_nop 0
	global_load_lds_dwordx4 v[182:183], off
	v_lshl_add_u64 v[182:183], s[28:29], 0, v[166:167]
	s_add_i32 m0, s30, 0x2000
	s_nop 0
	global_load_lds_dwordx4 v[182:183], off
	v_lshl_add_u64 v[182:183], v[186:187], 0, s[14:15]
	s_mov_b32 m0, s49
	s_nop 0
	global_load_lds_dwordx4 v[182:183], off
	v_lshl_add_u64 v[182:183], v[188:189], 0, s[14:15]
	s_mov_b32 m0, s50
	s_nop 0
	global_load_lds_dwordx4 v[182:183], off
	s_waitcnt vmcnt(8)
	s_waitcnt lgkmcnt(0)
	s_setprio 1
	s_barrier
	v_mfma_scale_f32_16x16x128_f8f6f4 v[124:127], v[0:7], v[196:203], v[124:127], v195, v195 op_sel_hi:[0,0,0]
	v_mfma_scale_f32_16x16x128_f8f6f4 v[120:123], v[8:15], v[196:203], v[120:123], v195, v195 op_sel_hi:[0,0,0]
	v_mfma_scale_f32_16x16x128_f8f6f4 v[116:119], v[0:7], v[204:211], v[116:119], v195, v195 op_sel_hi:[0,0,0]
	v_mfma_scale_f32_16x16x128_f8f6f4 v[112:115], v[8:15], v[204:211], v[112:115], v195, v195 op_sel_hi:[0,0,0]
	v_mfma_scale_f32_16x16x128_f8f6f4 v[108:111], v[0:7], v[212:219], v[108:111], v195, v195 op_sel_hi:[0,0,0]
	v_mfma_scale_f32_16x16x128_f8f6f4 v[104:107], v[8:15], v[212:219], v[104:107], v195, v195 op_sel_hi:[0,0,0]
	v_mfma_scale_f32_16x16x128_f8f6f4 v[100:103], v[0:7], v[220:227], v[100:103], v195, v195 op_sel_hi:[0,0,0]
	v_mfma_scale_f32_16x16x128_f8f6f4 v[96:99], v[8:15], v[220:227], v[96:99], v195, v195 op_sel_hi:[0,0,0]
	s_setprio 0
	s_setprio 1
	v_mfma_scale_f32_16x16x128_f8f6f4 v[60:63], v[16:23], v[196:203], v[60:63], v195, v195 op_sel_hi:[0,0,0]
	v_mfma_scale_f32_16x16x128_f8f6f4 v[56:59], v[24:31], v[196:203], v[56:59], v195, v195 op_sel_hi:[0,0,0]
	v_mfma_scale_f32_16x16x128_f8f6f4 v[52:55], v[16:23], v[204:211], v[52:55], v195, v195 op_sel_hi:[0,0,0]
	v_mfma_scale_f32_16x16x128_f8f6f4 v[48:51], v[24:31], v[204:211], v[48:51], v195, v195 op_sel_hi:[0,0,0]
	v_mfma_scale_f32_16x16x128_f8f6f4 v[44:47], v[16:23], v[212:219], v[44:47], v195, v195 op_sel_hi:[0,0,0]
	v_mfma_scale_f32_16x16x128_f8f6f4 v[40:43], v[24:31], v[212:219], v[40:43], v195, v195 op_sel_hi:[0,0,0]
	v_mfma_scale_f32_16x16x128_f8f6f4 v[36:39], v[16:23], v[220:227], v[36:39], v195, v195 op_sel_hi:[0,0,0]
	v_mfma_scale_f32_16x16x128_f8f6f4 v[32:35], v[24:31], v[220:227], v[32:35], v195, v195 op_sel_hi:[0,0,0]
	s_setprio 0
	s_barrier
	s_add_i32 s62, s62, 2
	s_add_u32 s26, s26, 0x100
	s_addc_u32 s27, s27, 0
	s_cmp_gt_u32 s62, 13
	s_cbranch_scc0 .LBB0_818
	s_add_u32 s26, s23, 0xffffff00
	s_addc_u32 s27, s59, -1
	s_andn2_b64 vcc, exec, s[4:5]
	s_cbranch_vccnz .LBB0_809
	v_mov_b32_e32 v32, 0
	s_mov_b32 s6, s16
	s_mov_b32 s10, s18
	s_mov_b64 s[12:13], s[24:25]
	s_mov_b32 s48, s22
	v_mov_b32_e32 v33, v32
	v_mov_b32_e32 v34, v32
	v_mov_b32_e32 v35, v32
	v_mov_b32_e32 v36, v32
	v_mov_b32_e32 v37, v32
	v_mov_b32_e32 v38, v32
	v_mov_b32_e32 v39, v32
	v_mov_b32_e32 v40, v32
	v_mov_b32_e32 v41, v32
	v_mov_b32_e32 v42, v32
	v_mov_b32_e32 v43, v32
	v_mov_b32_e32 v44, v32
	v_mov_b32_e32 v45, v32
	v_mov_b32_e32 v46, v32
	v_mov_b32_e32 v47, v32
	v_mov_b32_e32 v48, v32
	v_mov_b32_e32 v49, v32
	v_mov_b32_e32 v50, v32
	v_mov_b32_e32 v51, v32
	v_mov_b32_e32 v52, v32
	v_mov_b32_e32 v53, v32
	v_mov_b32_e32 v54, v32
	v_mov_b32_e32 v55, v32
	v_mov_b32_e32 v56, v32
	v_mov_b32_e32 v57, v32
	v_mov_b32_e32 v58, v32
	v_mov_b32_e32 v59, v32
	v_mov_b32_e32 v60, v32
	v_mov_b32_e32 v61, v32
	v_mov_b32_e32 v62, v32
	v_mov_b32_e32 v63, v32
	v_mov_b32_e32 v96, v32
	v_mov_b32_e32 v97, v32
	v_mov_b32_e32 v98, v32
	v_mov_b32_e32 v99, v32
	v_mov_b32_e32 v100, v32
	v_mov_b32_e32 v101, v32
	v_mov_b32_e32 v102, v32
	v_mov_b32_e32 v103, v32
	v_mov_b32_e32 v104, v32
	v_mov_b32_e32 v105, v32
	v_mov_b32_e32 v106, v32
	v_mov_b32_e32 v107, v32
	v_mov_b32_e32 v108, v32
	v_mov_b32_e32 v109, v32
	v_mov_b32_e32 v110, v32
	v_mov_b32_e32 v111, v32
	v_mov_b32_e32 v112, v32
	v_mov_b32_e32 v113, v32
	v_mov_b32_e32 v114, v32
	v_mov_b32_e32 v115, v32
	v_mov_b32_e32 v116, v32
	v_mov_b32_e32 v117, v32
	v_mov_b32_e32 v118, v32
	v_mov_b32_e32 v119, v32
	v_mov_b32_e32 v120, v32
	v_mov_b32_e32 v121, v32
	v_mov_b32_e32 v122, v32
	v_mov_b32_e32 v123, v32
	v_mov_b32_e32 v124, v32
	v_mov_b32_e32 v125, v32
	v_mov_b32_e32 v126, v32
	v_mov_b32_e32 v127, v32
	v_mov_b32_e32 v64, v32
	v_mov_b32_e32 v65, v32
	v_mov_b32_e32 v66, v32
	v_mov_b32_e32 v67, v32
	v_mov_b32_e32 v68, v32
	v_mov_b32_e32 v69, v32
	v_mov_b32_e32 v70, v32
	v_mov_b32_e32 v71, v32
	v_mov_b32_e32 v72, v32
	v_mov_b32_e32 v73, v32
	v_mov_b32_e32 v74, v32
	v_mov_b32_e32 v75, v32
	v_mov_b32_e32 v76, v32
	v_mov_b32_e32 v77, v32
	v_mov_b32_e32 v78, v32
	v_mov_b32_e32 v79, v32
	v_mov_b32_e32 v80, v32
	v_mov_b32_e32 v81, v32
	v_mov_b32_e32 v82, v32
	v_mov_b32_e32 v83, v32
	v_mov_b32_e32 v84, v32
	v_mov_b32_e32 v85, v32
	v_mov_b32_e32 v86, v32
	v_mov_b32_e32 v87, v32
	v_mov_b32_e32 v88, v32
	v_mov_b32_e32 v89, v32
	v_mov_b32_e32 v90, v32
	v_mov_b32_e32 v91, v32
	v_mov_b32_e32 v92, v32
	v_mov_b32_e32 v93, v32
	v_mov_b32_e32 v94, v32
	v_mov_b32_e32 v95, v32
	v_mov_b32_e32 v128, v32
	v_mov_b32_e32 v129, v32
	v_mov_b32_e32 v130, v32
	v_mov_b32_e32 v131, v32
	v_mov_b32_e32 v132, v32
	v_mov_b32_e32 v133, v32
	v_mov_b32_e32 v134, v32
	v_mov_b32_e32 v135, v32
	v_mov_b32_e32 v136, v32
	v_mov_b32_e32 v137, v32
	v_mov_b32_e32 v138, v32
	v_mov_b32_e32 v139, v32
	v_mov_b32_e32 v140, v32
	v_mov_b32_e32 v141, v32
	v_mov_b32_e32 v142, v32
	v_mov_b32_e32 v143, v32
	v_mov_b32_e32 v144, v32
	v_mov_b32_e32 v145, v32
	v_mov_b32_e32 v146, v32
	v_mov_b32_e32 v147, v32
	v_mov_b32_e32 v148, v32
	v_mov_b32_e32 v149, v32
	v_mov_b32_e32 v150, v32
	v_mov_b32_e32 v151, v32
	v_mov_b32_e32 v152, v32
	v_mov_b32_e32 v153, v32
	v_mov_b32_e32 v154, v32
	v_mov_b32_e32 v155, v32
	v_mov_b32_e32 v156, v32
	v_mov_b32_e32 v157, v32
	v_mov_b32_e32 v158, v32
	v_mov_b32_e32 v159, v32
	s_andn2_b64 vcc, exec, s[0:1]
	s_cbranch_vccnz .LBB0_810
